# v11: + NA/ctx epilogue gate (z) loads prefetched at task start, sw_tasks reductions interleaved + row prefetch, counted vmcnt waits on the K/V register ring
# speedup vs baseline: 1.0279x; 1.0045x over previous
.LBB0_1001:
	s_add_u32 s50, s46, 0x67fe000
	s_addc_u32 s51, s47, 0
	s_movk_i32 s4, 0x90
	v_readlane_b32 s38, v254, 43
	s_add_u32 s36, s46, 0x73fe000
	v_mul_lo_u32 v1, v132, s4
	v_readlane_b32 s39, v254, 44
	s_addc_u32 s37, s47, 0
	v_add3_u32 v207, v1, v110, 0
	s_mov_b64 s[10:11], -1
	s_andn2_b64 vcc, exec, s[38:39]
	v_lshlrev_b32_e32 v206, 2, v69
	s_barrier
	s_waitcnt vmcnt(5)
	ds_write_b128 v207, v[90:93] offset:15360
	s_waitcnt vmcnt(4)
	ds_write_b128 v207, v[98:101] offset:24576
	s_waitcnt lgkmcnt(0)
	s_barrier
	s_cbranch_vccnz .LBB0_1003
	v_lshlrev_b32_e32 v192, 2, v69
	s_mov_b64 s[10:11], 0
.LBB0_1003:
	s_add_u32 vcc_lo, s46, 0x8bfe000
	s_addc_u32 vcc_hi, s47, 0
	v_lshlrev_b64 v[176:177], 11, v[112:113]
	v_lshl_add_u64 v[176:177], vcc, 0, v[176:177]
	v_lshl_add_u64 v[176:177], v[176:177], 0, s[12:13]
	v_mov_b32_e32 v178, v206
	v_mov_b32_e32 v179, 0
	v_lshl_add_u64 v[176:177], v[178:179], 1, v[176:177]
	global_load_dwordx2 v[160:161], v[176:177], off
	global_load_dwordx2 v[162:163], v[176:177], off offset:16
	global_load_dwordx2 v[164:165], v[176:177], off offset:32
	global_load_dwordx2 v[166:167], v[176:177], off offset:48
	global_load_dwordx2 v[168:169], v[176:177], off offset:64
	global_load_dwordx2 v[170:171], v[176:177], off offset:80
	global_load_dwordx2 v[172:173], v[176:177], off offset:96
	global_load_dwordx2 v[174:175], v[176:177], off offset:112
	v_lshlrev_b32_e32 v134, 3, v0
	v_lshrrev_b32_e32 v0, 2, v212
	v_and_b32_e32 v1, 16, v212
	v_lshlrev_b32_e32 v2, 2, v213
	s_mov_b32 s4, 0
	s_andn2_b64 vcc, exec, s[10:11]
	v_mul_u32_u24_e32 v208, 0x90, v135
	v_or_b32_e32 v209, 32, v213
	v_and_or_b32 v115, v0, 3, v206
	v_and_or_b32 v120, v2, 12, v1
	s_cbranch_vccnz .LBB0_1401
	s_max_i32 s5, s5, 4
	s_add_i32 s5, s5, -4
	v_or_b32_e32 v0, s18, v135
	s_min_u32 s5, s5, 24
	v_sub_u32_e64 v1, v0, 8 clamp
	v_min_u32_e32 v1, 48, v1
	s_or_b32 s0, s0, 0x3000
	s_add_i32 s55, s5, 8
	v_sub_u32_e32 v0, v206, v0
	s_cmp_eq_u32 s17, 0
	v_sub_u32_e32 v121, v1, v206
	v_add_u32_e32 v122, 15, v0
	v_lshlrev_b64 v[0:1], 10, v[132:133]
	s_cselect_b64 s[18:19], -1, 0
	s_cmp_lg_u32 s17, 0
	v_lshl_add_u64 v[2:3], s[50:51], 0, v[0:1]
	v_mov_b32_e32 v111, v193
	v_lshl_add_u64 v[0:1], s[36:37], 0, v[0:1]
	s_mulk_i32 s16, 0xff84
	v_readlane_b32 s10, v255, 12
	v_mov_b32_e32 v16, v193
	v_mov_b32_e32 v17, v193
	s_cselect_b64 s[52:53], -1, 0
	v_lshl_add_u64 v[116:117], v[2:3], 0, v[110:111]
	v_lshl_add_u64 v[118:119], v[0:1], 0, v[110:111]
	s_add_i32 s64, s10, s16
	v_mov_b32_e32 v18, v193
	v_mov_b32_e32 v19, v193
	v_mov_b32_e32 v20, v193
	v_mov_b32_e32 v21, v193
	v_mov_b32_e32 v22, v193
	v_mov_b32_e32 v23, v193
	v_mov_b32_e32 v24, v193
	v_mov_b32_e32 v25, v193
	v_mov_b32_e32 v26, v193
	v_mov_b32_e32 v27, v193
	v_mov_b32_e32 v28, v193
	v_mov_b32_e32 v29, v193
	v_mov_b32_e32 v30, v193
	v_mov_b32_e32 v31, v193
	v_readlane_b32 s10, v255, 11
	v_mov_b64_e32 v[0:1], v[16:17]
	v_lshlrev_b32_e32 v123, 1, v120
	v_mul_u32_u24_e32 v124, 0x90, v209
	v_mul_u32_u24_e32 v125, 0x90, v115
	v_mov_b32_e32 v111, 0xf149f2ca
	v_mov_b32_e32 v32, 0
	v_lshlrev_b32_e32 v192, 1, v134
	s_mov_b32 s56, s10
	v_mov_b64_e32 v[2:3], v[18:19]
	v_mov_b64_e32 v[4:5], v[20:21]
	v_mov_b64_e32 v[6:7], v[22:23]
	v_mov_b64_e32 v[8:9], v[24:25]
	v_mov_b64_e32 v[10:11], v[26:27]
	v_mov_b64_e32 v[12:13], v[28:29]
	v_mov_b64_e32 v[14:15], v[30:31]
	s_mov_b32 s68, 0
	s_branch .LBB0_1007

.LBB0_1137:
	s_add_i32 s40, s68, 1
	s_cmp_lt_i32 s40, s25
	s_cselect_b64 s[10:11], -1, 0
	s_cmp_ge_i32 s40, s25
	s_cbranch_scc1 .LBB0_1139
	s_bitcmp1_b32 s40, 0
	s_cselect_b32 s16, 0x4800, 0
	v_add_u32_e32 v33, s16, v207
	s_andn2_b64 vcc, exec, s[62:63]
	s_cbranch_vccnz .Lw1_slow
	s_waitcnt vmcnt(5)
	ds_write_b128 v33, v[86:89] offset:15360
	s_waitcnt vmcnt(4)
	ds_write_b128 v33, v[94:97] offset:24576
	s_branch .LBB0_1139
.Lw1_slow:
	s_waitcnt vmcnt(1)
	ds_write_b128 v33, v[86:89] offset:15360
	s_waitcnt vmcnt(0)
	ds_write_b128 v33, v[94:97] offset:24576

.LBB0_1268:
	v_readlane_b32 s10, v254, 50
	s_cmp_ge_i32 s68, s10
	s_cbranch_scc1 .LBB0_1270
	s_bitcmp1_b32 s68, 0
	s_cselect_b32 s10, 0x4800, 0
	v_add_u32_e32 v33, s10, v207
	s_add_i32 s10, s68, 4
	s_cmp_lt_i32 s10, s25
	s_cbranch_scc0 .Lw2_slow
	s_waitcnt vmcnt(5)
	ds_write_b128 v33, v[102:105] offset:15360
	s_waitcnt vmcnt(4)
	ds_write_b128 v33, v[106:109] offset:24576
	s_branch .LBB0_1270
.Lw2_slow:
	s_waitcnt vmcnt(1)
	ds_write_b128 v33, v[102:105] offset:15360
	s_waitcnt vmcnt(0)
	ds_write_b128 v33, v[106:109] offset:24576

.LBB0_1398:
	s_bitcmp1_b32 s65, 0
	s_cselect_b32 s10, 0x4800, 0
	v_add_u32_e32 v33, s10, v207
	s_add_i32 s10, s68, 5
	s_cmp_lt_i32 s10, s25
	s_cbranch_scc0 .Lw3_slow
	s_waitcnt vmcnt(5)
	ds_write_b128 v33, v[90:93] offset:15360
	s_waitcnt vmcnt(4)
	ds_write_b128 v33, v[98:101] offset:24576
	s_branch .LBB0_1399
.Lw3_slow:
	s_waitcnt vmcnt(1)
	ds_write_b128 v33, v[90:93] offset:15360
	s_waitcnt vmcnt(0)
	ds_write_b128 v33, v[98:101] offset:24576

.LBB0_1402:
	s_add_u32 s0, s46, 0x8bfe000
	s_addc_u32 s1, s47, 0
	v_lshlrev_b64 v[34:35], 11, v[112:113]
	v_lshl_add_u64 v[34:35], s[0:1], 0, v[34:35]
	v_lshl_add_u64 v[34:35], v[34:35], 0, s[12:13]
	v_lshl_add_u64 v[34:35], v[192:193], 1, v[34:35]
	v_mov_b64_e32 v[36:37], v[160:161]
	v_mov_b64_e32 v[38:39], v[162:163]
	v_mov_b64_e32 v[40:41], v[164:165]
	v_mov_b64_e32 v[42:43], v[166:167]
	v_mov_b64_e32 v[44:45], v[168:169]
	v_cmp_lt_i32_e32 vcc, v222, v221
	v_mov_b64_e32 v[46:47], v[170:171]
	v_lshlrev_b32_e32 v140, 3, v69
	v_cndmask_b32_e32 v33, v220, v222, vcc
	v_lshlrev_b32_e32 v210, 2, v33
	ds_bpermute_b32 v33, v210, v32
	s_waitcnt lgkmcnt(0)
	v_add_f32_e32 v50, v32, v33
	v_mov_b64_e32 v[32:33], v[172:173]
	v_mov_b64_e32 v[48:49], v[174:175]
	v_div_scale_f32 v51, s[4:5], v50, v50, 1.0
	v_rcp_f32_e32 v52, v51
	v_div_scale_f32 v53, vcc, 1.0, v50, 1.0
	v_readlane_b32 s4, v254, 52
	v_fma_f32 v54, -v51, v52, 1.0
	v_fmac_f32_e32 v52, v54, v52
	v_mul_f32_e32 v54, v53, v52
	v_fma_f32 v55, -v51, v54, v53
	v_fmac_f32_e32 v54, v55, v52
	v_fma_f32 v51, -v51, v54, v53
	v_div_fmas_f32 v51, v51, v52, v54
	v_div_fixup_f32 v50, v51, v50, 1.0
	v_pk_mul_f32 v[16:17], v[16:17], v[50:51] op_sel_hi:[1,0]
	v_pk_mul_f32 v[18:19], v[18:19], v[50:51] op_sel_hi:[1,0]
	v_pk_mul_f32 v[0:1], v[0:1], v[50:51] op_sel_hi:[1,0]
	v_pk_mul_f32 v[2:3], v[2:3], v[50:51] op_sel_hi:[1,0]
	v_pk_mul_f32 v[20:21], v[20:21], v[50:51] op_sel_hi:[1,0]
	v_pk_mul_f32 v[22:23], v[22:23], v[50:51] op_sel_hi:[1,0]
	v_pk_mul_f32 v[24:25], v[24:25], v[50:51] op_sel_hi:[1,0]
	v_pk_mul_f32 v[26:27], v[26:27], v[50:51] op_sel_hi:[1,0]
	v_pk_mul_f32 v[28:29], v[28:29], v[50:51] op_sel_hi:[1,0]
	v_pk_mul_f32 v[30:31], v[30:31], v[50:51] op_sel_hi:[1,0]
	v_pk_mul_f32 v[4:5], v[4:5], v[50:51] op_sel_hi:[1,0]
	v_readlane_b32 s5, v254, 53
	s_andn2_b64 vcc, exec, s[4:5]
	s_waitcnt vmcnt(7)
	v_lshlrev_b32_e32 v52, 16, v36
	v_and_b32_e32 v53, 0xffff0000, v36
	v_lshlrev_b32_e32 v36, 16, v37
	v_and_b32_e32 v37, 0xffff0000, v37
	s_waitcnt vmcnt(3)
	v_lshlrev_b32_e32 v60, 16, v44
	v_and_b32_e32 v61, 0xffff0000, v44
	v_lshlrev_b32_e32 v44, 16, v45
	v_and_b32_e32 v45, 0xffff0000, v45
	v_lshlrev_b32_e32 v54, 16, v38
	v_and_b32_e32 v55, 0xffff0000, v38
	v_lshlrev_b32_e32 v38, 16, v39
	v_and_b32_e32 v39, 0xffff0000, v39
	v_lshlrev_b32_e32 v56, 16, v40
	v_and_b32_e32 v57, 0xffff0000, v40
	v_lshlrev_b32_e32 v40, 16, v41
	v_and_b32_e32 v41, 0xffff0000, v41
	v_lshlrev_b32_e32 v58, 16, v42
	v_and_b32_e32 v59, 0xffff0000, v42
	v_lshlrev_b32_e32 v42, 16, v43
	v_and_b32_e32 v43, 0xffff0000, v43
	v_pk_mul_f32 v[16:17], v[16:17], v[52:53]
	v_pk_mul_f32 v[18:19], v[18:19], v[36:37]
	v_pk_mul_f32 v[0:1], v[0:1], v[60:61]
	v_pk_mul_f32 v[2:3], v[2:3], v[44:45]
	v_pk_mul_f32 v[20:21], v[20:21], v[54:55]
	v_pk_mul_f32 v[22:23], v[22:23], v[38:39]
	v_pk_mul_f32 v[24:25], v[24:25], v[56:57]
	v_pk_mul_f32 v[26:27], v[26:27], v[40:41]
	v_pk_mul_f32 v[28:29], v[28:29], v[58:59]
	v_pk_mul_f32 v[30:31], v[30:31], v[42:43]
	v_cvt_pk_bf16_f32 v16, v16, v17
	v_cvt_pk_bf16_f32 v17, v18, v19
	v_cvt_pk_bf16_f32 v0, v0, v1
	v_cvt_pk_bf16_f32 v1, v2, v3
	v_cvt_pk_bf16_f32 v18, v20, v21
	v_cvt_pk_bf16_f32 v19, v22, v23
	v_cvt_pk_bf16_f32 v20, v24, v25
	v_cvt_pk_bf16_f32 v21, v26, v27
	v_cvt_pk_bf16_f32 v22, v28, v29
	v_cvt_pk_bf16_f32 v23, v30, v31
	global_store_dwordx2 v[34:35], v[16:17], off
	global_store_dwordx2 v[34:35], v[18:19], off offset:16
	global_store_dwordx2 v[34:35], v[20:21], off offset:32
	global_store_dwordx2 v[34:35], v[22:23], off offset:48
	global_store_dwordx2 v[34:35], v[0:1], off offset:64
	s_waitcnt vmcnt(7)
	v_lshlrev_b32_e32 v0, 16, v46
	v_and_b32_e32 v1, 0xffff0000, v46
	v_pk_mul_f32 v[0:1], v[4:5], v[0:1]
	v_pk_mul_f32 v[2:3], v[6:7], v[50:51] op_sel_hi:[1,0]
	v_lshlrev_b32_e32 v4, 16, v47
	v_and_b32_e32 v5, 0xffff0000, v47
	v_pk_mul_f32 v[2:3], v[2:3], v[4:5]
	v_cvt_pk_bf16_f32 v0, v0, v1
	v_cvt_pk_bf16_f32 v1, v2, v3
	global_store_dwordx2 v[34:35], v[0:1], off offset:80
	v_pk_mul_f32 v[0:1], v[8:9], v[50:51] op_sel_hi:[1,0]
	s_waitcnt vmcnt(7)
	v_lshlrev_b32_e32 v2, 16, v32
	v_and_b32_e32 v3, 0xffff0000, v32
	v_pk_mul_f32 v[0:1], v[0:1], v[2:3]
	v_pk_mul_f32 v[2:3], v[10:11], v[50:51] op_sel_hi:[1,0]
	v_lshlrev_b32_e32 v4, 16, v33
	v_and_b32_e32 v5, 0xffff0000, v33
	v_pk_mul_f32 v[2:3], v[2:3], v[4:5]
	v_cvt_pk_bf16_f32 v0, v0, v1
	v_cvt_pk_bf16_f32 v1, v2, v3
	global_store_dwordx2 v[34:35], v[0:1], off offset:96
	v_pk_mul_f32 v[0:1], v[12:13], v[50:51] op_sel_hi:[1,0]
	s_waitcnt vmcnt(7)
	v_lshlrev_b32_e32 v2, 16, v48
	v_and_b32_e32 v3, 0xffff0000, v48
	v_pk_mul_f32 v[0:1], v[0:1], v[2:3]
	v_pk_mul_f32 v[2:3], v[14:15], v[50:51] op_sel_hi:[1,0]
	v_lshlrev_b32_e32 v4, 16, v49
	v_and_b32_e32 v5, 0xffff0000, v49
	v_pk_mul_f32 v[2:3], v[2:3], v[4:5]
	v_cvt_pk_bf16_f32 v0, v0, v1
	v_cvt_pk_bf16_f32 v1, v2, v3
	global_store_dwordx2 v[34:35], v[0:1], off offset:112
	s_cbranch_vccnz .LBB0_1405
	s_lshl_b32 s4, s54, 5
	v_readlane_b32 s10, v254, 54
	s_add_i32 s5, s4, s10
	v_readlane_b32 s16, v255, 13
	v_readlane_b32 s11, v254, 55
	v_readlane_b32 s17, v255, 14
	s_add_u32 s10, s50, s16
	s_addc_u32 s11, s51, s17
	s_add_u32 s16, s36, s16
	s_addc_u32 s17, s37, s17
	v_lshlrev_b64 v[54:55], 10, v[132:133]
	v_lshl_add_u64 v[0:1], s[10:11], 0, v[54:55]
	v_mov_b32_e32 v111, v193
	v_lshl_add_u64 v[2:3], s[16:17], 0, v[54:55]
	v_lshl_add_u64 v[0:1], v[0:1], 0, v[110:111]
	v_lshl_add_u64 v[4:5], v[2:3], 0, v[110:111]
	global_load_dwordx4 v[0:3], v[0:1], off
	s_nop 0
	global_load_dwordx4 v[4:7], v[4:5], off
	v_or_b32_e32 v142, s5, v135
	v_ashrrev_i32_e32 v143, 31, v142
	v_readlane_b32 s18, v255, 33
	v_lshlrev_b64 v[8:9], 10, v[142:143]
	v_readlane_b32 s19, v255, 34
	v_lshl_add_u64 v[8:9], s[20:21], 0, v[8:9]
	s_mov_b32 s19, s13
	v_lshlrev_b64 v[234:235], 11, v[142:143]
	v_mov_b32_e32 v224, v140
	v_mov_b32_e32 v225, 0
	v_lshl_add_u64 v[234:235], s[0:1], 0, v[234:235]
	v_lshl_add_u64 v[234:235], v[234:235], 0, s[18:19]
	v_lshl_add_u64 v[234:235], v[234:235], 0, v[224:225]
	global_load_dwordx2 v[224:225], v[234:235], off
	global_load_dwordx2 v[226:227], v[234:235], off offset:16
	global_load_dwordx2 v[246:247], v[234:235], off offset:32
	global_load_dwordx2 v[248:249], v[234:235], off offset:48
	global_load_dwordx2 v[214:215], v[234:235], off offset:64
	global_load_dwordx2 v[216:217], v[234:235], off offset:80
	global_load_dwordx2 v[230:231], v[234:235], off offset:96
	global_load_dwordx2 v[232:233], v[234:235], off offset:112
	v_mov_b32_e32 v234, 0x7ffff800
	v_mov_b32_e32 v235, 0xffffff00
	v_lshl_add_u64 v[8:9], v[8:9], 0, s[18:19]
	v_lshlrev_b32_e32 v192, 1, v140
	v_lshl_add_u64 v[8:9], v[8:9], 0, v[192:193]
	global_load_dwordx4 v[92:95], v[8:9], off
	global_load_dwordx4 v[88:91], v[8:9], off offset:32
	global_load_dwordx4 v[84:87], v[8:9], off offset:64
	global_load_dwordx4 v[96:99], v[8:9], off offset:96
	v_readlane_b32 s16, v255, 15
	v_readlane_b32 s17, v255, 16
	s_add_u32 s10, s50, s16
	s_addc_u32 s11, s51, s17
	s_add_u32 s16, s36, s16
	v_lshl_add_u64 v[8:9], s[10:11], 0, v[54:55]
	s_addc_u32 s17, s37, s17
	v_lshl_add_u64 v[8:9], v[8:9], 0, v[110:111]
	v_lshl_add_u64 v[10:11], s[16:17], 0, v[54:55]
	v_lshl_add_u64 v[10:11], v[10:11], 0, v[110:111]
	global_load_dwordx4 v[16:19], v[8:9], off
	global_load_dwordx4 v[38:41], v[10:11], off
	v_readlane_b32 s16, v255, 17
	v_readlane_b32 s17, v255, 18
	s_add_u32 s10, s50, s16
	s_addc_u32 s11, s51, s17
	s_add_u32 s16, s36, s16
	v_lshl_add_u32 v237, v69, 4, 0
	s_movk_i32 s5, 0x90
	v_lshl_add_u64 v[8:9], s[10:11], 0, v[54:55]
	s_addc_u32 s17, s37, s17
	v_mad_u32_u24 v141, v209, s5, v237
	v_lshl_add_u64 v[8:9], v[8:9], 0, v[110:111]
	v_lshl_add_u64 v[10:11], s[16:17], 0, v[54:55]
	v_lshl_add_u64 v[10:11], v[10:11], 0, v[110:111]
	global_load_dwordx4 v[66:69], v[8:9], off
	global_load_dwordx4 v[70:73], v[10:11], off
	s_barrier
	v_mad_u32_u24 v238, v135, s5, v237
	v_readlane_b32 s10, v255, 19
	v_readlane_b32 s11, v255, 20
	s_waitcnt vmcnt(9)
	ds_write_b128 v207, v[0:3] offset:15360
	s_waitcnt vmcnt(8)
	ds_write_b128 v207, v[4:7] offset:24576
	s_waitcnt lgkmcnt(0)
	s_barrier
	ds_read_b128 v[0:3], v141 offset:15360
	ds_read_b128 v[42:45], v141 offset:15392
	s_waitcnt vmcnt(7) lgkmcnt(1)
	v_mfma_f32_32x32x16_bf16 v[0:15], v[0:3], v[92:95], 0
	ds_read_b128 v[20:23], v238 offset:15360
	ds_read_b128 v[46:49], v238 offset:15392
	s_waitcnt lgkmcnt(1)
	v_mfma_f32_32x32x16_bf16 v[22:37], v[20:23], v[92:95], 0
	v_lshl_add_u64 v[20:21], s[50:51], 0, v[54:55]
	v_lshl_add_u64 v[136:137], v[20:21], 0, v[110:111]
	s_waitcnt vmcnt(6)
	v_mfma_f32_32x32x16_bf16 v[0:15], v[42:45], v[88:91], v[0:15]
	s_waitcnt lgkmcnt(0)
	v_mfma_f32_32x32x16_bf16 v[22:37], v[46:49], v[88:91], v[22:37]
	ds_read_b128 v[42:45], v141 offset:15424
	ds_read_b128 v[46:49], v141 offset:15456
	s_waitcnt vmcnt(5) lgkmcnt(1)
	v_mfma_f32_32x32x16_bf16 v[0:15], v[42:45], v[84:87], v[0:15]
	ds_read_b128 v[42:45], v238 offset:15424
	ds_read_b128 v[50:53], v238 offset:15456
	s_waitcnt lgkmcnt(1)
	v_mfma_f32_32x32x16_bf16 v[22:37], v[42:45], v[84:87], v[22:37]
	v_lshl_add_u64 v[42:43], s[36:37], 0, v[54:55]
	v_lshl_add_u64 v[138:139], v[42:43], 0, v[110:111]
	v_lshlrev_b32_e32 v44, 1, v120
	v_mul_u32_u24_e32 v45, 0x90, v115
	v_add3_u32 v211, 0, v44, v45
	s_waitcnt vmcnt(4) lgkmcnt(0)
	v_mfma_f32_32x32x16_bf16 v[22:37], v[50:53], v[96:99], v[22:37]
	v_mfma_f32_32x32x16_bf16 v[0:15], v[46:49], v[96:99], v[0:15]
	s_nop 10
	v_max_f32_e32 v20, v23, v23
	v_max_f32_e32 v21, v22, v22
	v_max_f32_e32 v42, v25, v25
	v_max_f32_e32 v43, v24, v24
	v_max_f32_e32 v20, v21, v20
	v_max_f32_e32 v21, v43, v42
	v_max_f32_e32 v50, v27, v27
	v_max_f32_e32 v46, v1, v1
	v_max_f32_e32 v47, v0, v0
	v_max_f32_e32 v48, v3, v3
	v_max_f32_e32 v49, v2, v2
	v_max_f32_e32 v51, v26, v26
	v_max_f32_e32 v52, v29, v29
	v_max_f32_e32 v53, v28, v28
	v_max_f32_e32 v42, v47, v46
	v_max_f32_e32 v43, v49, v48
	v_max3_f32 v20, v20, s23, v21
	v_max_f32_e32 v54, v5, v5
	v_max_f32_e32 v55, v4, v4
	v_max_f32_e32 v56, v7, v7
	v_max_f32_e32 v57, v6, v6
	v_max_f32_e32 v46, v51, v50
	v_max_f32_e32 v47, v53, v52
	v_max3_f32 v20, v20, v42, v43
	v_max_f32_e32 v58, v31, v31
	v_max_f32_e32 v59, v30, v30
	v_max_f32_e32 v60, v33, v33
	v_max_f32_e32 v61, v32, v32
	v_max_f32_e32 v48, v55, v54
	v_max_f32_e32 v49, v57, v56
	v_max3_f32 v20, v20, v46, v47
	v_max_f32_e32 v62, v9, v9
	v_max_f32_e32 v63, v8, v8
	v_max_f32_e32 v64, v11, v11
	v_max_f32_e32 v65, v10, v10
	v_max_f32_e32 v50, v59, v58
	v_max_f32_e32 v51, v61, v60
	v_max3_f32 v20, v20, v48, v49
	v_max_f32_e32 v74, v35, v35
	v_max_f32_e32 v75, v34, v34
	v_max_f32_e32 v76, v37, v37
	v_max_f32_e32 v77, v36, v36
	v_max_f32_e32 v52, v63, v62
	v_max_f32_e32 v53, v65, v64
	v_max3_f32 v20, v20, v50, v51
	v_max_f32_e32 v78, v13, v13
	v_max_f32_e32 v79, v12, v12
	v_max_f32_e32 v80, v15, v15
	v_max_f32_e32 v81, v14, v14
	v_max_f32_e32 v54, v75, v74
	v_max_f32_e32 v55, v77, v76
	v_max3_f32 v20, v20, v52, v53
	v_max_f32_e32 v56, v79, v78
	v_max_f32_e32 v57, v81, v80
	v_max3_f32 v20, v20, v54, v55
	v_max3_f32 v46, v20, v56, v57
	ds_bpermute_b32 v47, v210, v46
	v_lshl_add_u64 v[42:43], v[136:137], 0, s[10:11]
	v_lshl_add_u64 v[20:21], v[138:139], 0, s[10:11]
	global_load_dwordx4 v[100:103], v[42:43], off
	global_load_dwordx4 v[104:107], v[20:21], off
	ds_read_b64_tr_b16 v[128:129], v211 offset:24576
	ds_read_b64_tr_b16 v[130:131], v211 offset:25728
	ds_read_b64_tr_b16 v[126:127], v211 offset:25792
	ds_read_b64_tr_b16 v[124:125], v211 offset:24640
	ds_read_b64_tr_b16 v[120:121], v211 offset:26880
	ds_read_b64_tr_b16 v[122:123], v211 offset:28032
	ds_read_b64_tr_b16 v[118:119], v211 offset:28096
	ds_read_b64_tr_b16 v[116:117], v211 offset:26944
	ds_read_b64_tr_b16 v[112:113], v211 offset:29184
	ds_read_b64_tr_b16 v[114:115], v211 offset:30336
	ds_read_b64_tr_b16 v[110:111], v211 offset:30400
	ds_read_b64_tr_b16 v[108:109], v211 offset:29248
	ds_read_b64_tr_b16 v[78:79], v211 offset:31488
	ds_read_b64_tr_b16 v[80:81], v211 offset:32640
	ds_read_b64_tr_b16 v[76:77], v211 offset:32704
	ds_read_b64_tr_b16 v[74:75], v211 offset:31552
	s_waitcnt lgkmcnt(14)
	v_max3_f32 v52, v46, v47, s23
	v_sub_f32_e32 v0, v0, v52
	v_exp_f32_e32 v150, v0
	v_sub_f32_e32 v0, v1, v52
	v_exp_f32_e32 v154, v0
	v_sub_f32_e32 v0, v2, v52
	v_exp_f32_e32 v144, v0
	v_sub_f32_e32 v0, v3, v52
	v_exp_f32_e32 v148, v0
	v_sub_f32_e32 v0, v26, v52
	v_exp_f32_e32 v152, v0
	v_sub_f32_e32 v0, v27, v52
	v_exp_f32_e32 v156, v0
	v_sub_f32_e32 v0, v28, v52
	v_exp_f32_e32 v160, v0
	v_sub_f32_e32 v0, v29, v52
	v_exp_f32_e32 v162, v0
	v_sub_f32_e32 v0, v4, v52
	v_exp_f32_e32 v158, v0
	v_sub_f32_e32 v0, v5, v52
	v_exp_f32_e32 v164, v0
	s_waitcnt vmcnt(5)
	ds_write_b128 v207, v[16:19] offset:33792
	s_waitcnt vmcnt(4)
	ds_write_b128 v207, v[38:41] offset:43008
	s_waitcnt lgkmcnt(0)
	s_barrier
	ds_read_b128 v[0:3], v141 offset:33792
	v_sub_f32_e32 v4, v6, v52
	v_exp_f32_e32 v168, v4
	v_sub_f32_e32 v4, v7, v52
	v_sub_f32_e32 v20, v22, v52
	v_exp_f32_e32 v170, v4
	v_sub_f32_e32 v4, v30, v52
	v_sub_f32_e32 v21, v23, v52
	v_sub_f32_e32 v22, v24, v52
	v_exp_f32_e32 v240, v20
	v_sub_f32_e32 v20, v25, v52
	v_exp_f32_e32 v172, v4
	ds_read_b128 v[4:7], v141 offset:33824
	v_exp_f32_e32 v239, v21
	v_exp_f32_e32 v82, v22
	v_exp_f32_e32 v146, v20
	v_sub_f32_e32 v38, v31, v52
	s_waitcnt lgkmcnt(1)
	v_mfma_f32_32x32x16_bf16 v[16:31], v[0:3], v[92:95], 0
	v_sub_f32_e32 v0, v32, v52
	v_exp_f32_e32 v174, v0
	v_sub_f32_e32 v0, v33, v52
	v_exp_f32_e32 v176, v0
	ds_read_b128 v[0:3], v141 offset:33856
	v_sub_f32_e32 v8, v8, v52
	v_exp_f32_e32 v180, v8
	s_waitcnt lgkmcnt(1)
	v_mfma_f32_32x32x16_bf16 v[16:31], v[4:7], v[88:91], v[16:31]
	v_sub_f32_e32 v4, v9, v52
	v_exp_f32_e32 v182, v4
	v_sub_f32_e32 v4, v10, v52
	v_exp_f32_e32 v184, v4
	ds_read_b128 v[4:7], v141 offset:33888
	v_sub_f32_e32 v8, v11, v52
	v_exp_f32_e32 v178, v38
	s_waitcnt lgkmcnt(1)
	v_mfma_f32_32x32x16_bf16 v[16:31], v[0:3], v[84:87], v[16:31]
	v_sub_f32_e32 v0, v34, v52
	v_exp_f32_e32 v186, v0
	v_sub_f32_e32 v0, v35, v52
	v_exp_f32_e32 v188, v0
	ds_read_b128 v[0:3], v238 offset:33792
	v_exp_f32_e32 v190, v8
	v_sub_f32_e32 v8, v36, v52
	s_waitcnt lgkmcnt(1)
	v_mfma_f32_32x32x16_bf16 v[16:31], v[4:7], v[96:99], v[16:31]
	v_sub_f32_e32 v4, v37, v52
	v_exp_f32_e32 v198, v4
	v_sub_f32_e32 v4, v12, v52
	v_exp_f32_e32 v200, v4
	ds_read_b128 v[4:7], v238 offset:33824
	v_exp_f32_e32 v196, v8
	v_sub_f32_e32 v8, v13, v52
	s_waitcnt lgkmcnt(1)
	v_mfma_f32_32x32x16_bf16 v[32:47], v[0:3], v[92:95], 0
	v_exp_f32_e32 v202, v8
	ds_read_b128 v[8:11], v238 offset:33856
	v_sub_f32_e32 v48, 0xf149f2ca, v52
	v_exp_f32_e32 v1, v48
	ds_read_b128 v[48:51], v238 offset:33888
	v_sub_f32_e32 v0, v14, v52
	v_exp_f32_e32 v204, v0
	s_waitcnt lgkmcnt(2)
	v_mfma_f32_32x32x16_bf16 v[32:47], v[4:7], v[88:91], v[32:47]
	v_sub_f32_e32 v0, v15, v52
	v_exp_f32_e32 v166, v0
	v_mul_f32_e32 v0, 0, v1
	v_mov_b32_e32 v1, v0
	v_mov_b32_e32 v2, v0
	v_mov_b32_e32 v3, v0
	v_mov_b32_e32 v4, v0
	s_waitcnt lgkmcnt(1)
	v_mfma_f32_32x32x16_bf16 v[32:47], v[8:11], v[84:87], v[32:47]
	v_mov_b32_e32 v5, v0
	v_mov_b32_e32 v6, v0
	v_mov_b32_e32 v7, v0
	v_mov_b32_e32 v8, v0
	v_mov_b32_e32 v9, v0
	v_mov_b32_e32 v10, v0
	v_mov_b32_e32 v11, v0
	s_waitcnt lgkmcnt(0)
	v_mfma_f32_32x32x16_bf16 v[32:47], v[48:51], v[96:99], v[32:47]
	v_max_f32_e32 v48, v18, v18
	v_mov_b32_e32 v12, v0
	v_cvt_pk_bf16_f32 v242, v240, v239
	v_cvt_pk_bf16_f32 v243, v82, v146
	v_cvt_pk_bf16_f32 v244, v152, v156
	v_cvt_pk_bf16_f32 v245, v160, v162
	s_mov_b32 s10, s18
	s_nop 4
	v_max_f32_e32 v13, v33, v33
	v_max_f32_e32 v14, v32, v32
	v_max_f32_e32 v13, v14, v13
	v_max_f32_e32 v14, v35, v35
	v_max_f32_e32 v15, v34, v34
	v_max_f32_e32 v14, v15, v14
	v_max3_f32 v13, v13, s23, v14
	v_max_f32_e32 v14, v17, v17
	v_max_f32_e32 v15, v16, v16
	v_max_f32_e32 v14, v15, v14
	v_max_f32_e32 v15, v19, v19
	v_max_f32_e32 v15, v48, v15
	v_max3_f32 v13, v13, v14, v15
	v_max_f32_e32 v14, v37, v37
	v_max_f32_e32 v15, v36, v36
	v_max_f32_e32 v14, v15, v14
	v_max_f32_e32 v15, v39, v39
	v_max_f32_e32 v48, v38, v38
	v_max_f32_e32 v15, v48, v15
	v_max3_f32 v13, v13, v14, v15
	v_max_f32_e32 v14, v21, v21
	v_max_f32_e32 v15, v20, v20
	v_max_f32_e32 v14, v15, v14
	v_max_f32_e32 v15, v23, v23
	v_max_f32_e32 v48, v22, v22
	v_max_f32_e32 v15, v48, v15
	v_max3_f32 v13, v13, v14, v15
	v_max_f32_e32 v14, v41, v41
	v_max_f32_e32 v15, v40, v40
	v_max_f32_e32 v14, v15, v14
	v_max_f32_e32 v15, v43, v43
	v_max_f32_e32 v48, v42, v42
	v_max_f32_e32 v15, v48, v15
	v_max3_f32 v13, v13, v14, v15
	v_max_f32_e32 v14, v25, v25
	v_max_f32_e32 v15, v24, v24
	v_max_f32_e32 v14, v15, v14
	v_max_f32_e32 v15, v27, v27
	v_max_f32_e32 v48, v26, v26
	v_max_f32_e32 v15, v48, v15
	v_max3_f32 v13, v13, v14, v15
	v_max_f32_e32 v14, v45, v45
	v_max_f32_e32 v15, v44, v44
	v_max_f32_e32 v14, v15, v14
	v_max_f32_e32 v15, v47, v47
	v_max_f32_e32 v48, v46, v46
	v_max_f32_e32 v15, v48, v15
	v_max3_f32 v13, v13, v14, v15
	v_max_f32_e32 v14, v29, v29
	v_max_f32_e32 v15, v28, v28
	v_max_f32_e32 v14, v15, v14
	v_max_f32_e32 v15, v31, v31
	v_max_f32_e32 v48, v30, v30
	v_max_f32_e32 v15, v48, v15
	v_max3_f32 v48, v13, v14, v15
	ds_bpermute_b32 v49, v210, v48
	v_mov_b32_e32 v13, v0
	v_mov_b32_e32 v14, v0
	v_mov_b32_e32 v15, v0
	v_writelane_b32 v255, s10, 33
	s_waitcnt lgkmcnt(0)
	v_max3_f32 v241, v52, v48, v49
	v_sub_f32_e32 v16, v16, v241
	v_exp_f32_e32 v145, v16
	v_sub_f32_e32 v16, v17, v241
	v_exp_f32_e32 v149, v16
	v_sub_f32_e32 v16, v18, v241
	v_exp_f32_e32 v153, v16
	v_sub_f32_e32 v16, v19, v241
	v_exp_f32_e32 v157, v16
	v_sub_f32_e32 v16, v36, v241
	v_exp_f32_e32 v161, v16
	v_sub_f32_e32 v16, v37, v241
	v_exp_f32_e32 v163, v16
	v_sub_f32_e32 v16, v38, v241
	v_exp_f32_e32 v159, v16
	v_sub_f32_e32 v16, v39, v241
	v_exp_f32_e32 v165, v16
	v_sub_f32_e32 v16, v20, v241
	v_exp_f32_e32 v169, v16
	v_sub_f32_e32 v16, v21, v241
	v_sub_f32_e32 v48, v52, v241
	v_mfma_f32_32x32x16_bf16 v[50:65], v[128:131], v[242:245], v[0:15]
	v_exp_f32_e32 v171, v16
	v_mov_b64_e32 v[16:17], v[14:15]
	v_sub_f32_e32 v18, v22, v241
	v_exp_f32_e32 v173, v18
	v_cvt_pk_bf16_f32 v18, v172, v178
	s_nop 1
	v_mov_b64_e32 v[14:15], v[12:13]
	v_mov_b64_e32 v[12:13], v[10:11]
	v_mov_b64_e32 v[10:11], v[8:9]
	v_mov_b64_e32 v[8:9], v[6:7]
	v_mov_b64_e32 v[6:7], v[4:5]
	v_mov_b64_e32 v[4:5], v[2:3]
	v_mov_b64_e32 v[2:3], v[0:1]
	v_cvt_pk_bf16_f32 v19, v174, v176
	v_cvt_pk_bf16_f32 v20, v186, v188
	v_mfma_f32_32x32x16_bf16 v[2:17], v[124:127], v[242:245], v[2:17]
	v_cvt_pk_bf16_f32 v21, v196, v198
	v_sub_f32_e32 v1, v23, v241
	v_exp_f32_e32 v179, v1
	v_sub_f32_e32 v1, v40, v241
	v_cvt_pk_bf16_f32 v22, v200, v202
	v_cvt_pk_bf16_f32 v23, v204, v166
	v_sub_f32_e32 v32, v32, v241
	v_mfma_f32_32x32x16_bf16 v[50:65], v[120:123], v[18:21], v[50:65]
	v_exp_f32_e32 v175, v1
	v_sub_f32_e32 v1, v41, v241
	v_exp_f32_e32 v83, v32
	v_sub_f32_e32 v32, v33, v241
	v_exp_f32_e32 v177, v1
	v_sub_f32_e32 v1, v42, v241
	v_exp_f32_e32 v147, v32
	v_mfma_f32_32x32x16_bf16 v[2:17], v[116:119], v[18:21], v[2:17]
	v_cvt_pk_bf16_f32 v18, v150, v154
	v_cvt_pk_bf16_f32 v19, v144, v148
	v_cvt_pk_bf16_f32 v20, v158, v164
	v_cvt_pk_bf16_f32 v21, v168, v170
	v_sub_f32_e32 v32, v34, v241
	v_exp_f32_e32 v181, v1
	v_sub_f32_e32 v1, v43, v241
	v_mfma_f32_32x32x16_bf16 v[50:65], v[112:115], v[18:21], v[50:65]
	v_exp_f32_e32 v151, v32
	v_sub_f32_e32 v32, v35, v241
	v_exp_f32_e32 v183, v1
	v_sub_f32_e32 v1, v24, v241
	v_exp_f32_e32 v155, v32
	v_exp_f32_e32 v185, v1
	v_sub_f32_e32 v1, v25, v241
	v_mfma_f32_32x32x16_bf16 v[2:17], v[108:111], v[18:21], v[2:17]
	v_cvt_pk_bf16_f32 v20, v180, v182
	v_cvt_pk_bf16_f32 v21, v184, v190
	v_exp_f32_e32 v18, v48
	v_exp_f32_e32 v191, v1
	v_sub_f32_e32 v1, v44, v241
	v_exp_f32_e32 v197, v1
	v_sub_f32_e32 v1, v45, v241
	v_mfma_f32_32x32x16_bf16 v[50:65], v[78:81], v[20:23], v[50:65]
	ds_read_b64_tr_b16 v[78:79], v211 offset:43008
	ds_read_b64_tr_b16 v[80:81], v211 offset:44160
	ds_read_b64_tr_b16 v[110:111], v211 offset:44224
	ds_read_b64_tr_b16 v[108:109], v211 offset:43072
	ds_read_b64_tr_b16 v[112:113], v211 offset:45312
	ds_read_b64_tr_b16 v[114:115], v211 offset:46464
	v_exp_f32_e32 v199, v1
	v_sub_f32_e32 v1, v46, v241
	v_exp_f32_e32 v201, v1
	v_sub_f32_e32 v1, v47, v241
	v_cvt_pk_bf16_f32 v116, v83, v147
	v_cvt_pk_bf16_f32 v117, v151, v155
	v_mfma_f32_32x32x16_bf16 v[2:17], v[74:77], v[20:23], v[2:17]
	v_cvt_pk_bf16_f32 v118, v161, v163
	v_cvt_pk_bf16_f32 v119, v159, v165
	v_mul_f32_e64 v48, v64, v18
	v_mul_f32_e64 v49, v65, v18
	v_mul_f32_e64 v46, v62, v18
	v_mul_f32_e64 v47, v63, v18
	v_pk_mul_f32 v[44:45], v[60:61], v[18:19] op_sel_hi:[1,0]
	v_pk_mul_f32 v[42:43], v[58:59], v[18:19] op_sel_hi:[1,0]
	v_pk_mul_f32 v[40:41], v[56:57], v[18:19] op_sel_hi:[1,0]
	v_pk_mul_f32 v[38:39], v[54:55], v[18:19] op_sel_hi:[1,0]
	v_pk_mul_f32 v[36:37], v[52:53], v[18:19] op_sel_hi:[1,0]
	v_pk_mul_f32 v[34:35], v[50:51], v[18:19] op_sel_hi:[1,0]
	v_pk_mul_f32 v[16:17], v[16:17], v[18:19] op_sel_hi:[1,0]
	v_pk_mul_f32 v[14:15], v[14:15], v[18:19] op_sel_hi:[1,0]
	v_pk_mul_f32 v[12:13], v[12:13], v[18:19] op_sel_hi:[1,0]
	v_pk_mul_f32 v[10:11], v[10:11], v[18:19] op_sel_hi:[1,0]
	v_pk_mul_f32 v[8:9], v[8:9], v[18:19] op_sel_hi:[1,0]
	v_pk_mul_f32 v[6:7], v[6:7], v[18:19] op_sel_hi:[1,0]
	v_pk_mul_f32 v[4:5], v[4:5], v[18:19] op_sel_hi:[1,0]
	v_pk_mul_f32 v[2:3], v[2:3], v[18:19] op_sel_hi:[1,0]
	s_waitcnt lgkmcnt(4)
	v_mfma_f32_32x32x16_bf16 v[34:49], v[78:81], v[116:119], v[34:49]
	v_exp_f32_e32 v203, v1
	ds_read_b64_tr_b16 v[22:23], v211 offset:46528
	ds_read_b64_tr_b16 v[20:21], v211 offset:45376
	v_cvt_pk_bf16_f32 v50, v175, v177
	v_cvt_pk_bf16_f32 v51, v181, v183
	v_cvt_pk_bf16_f32 v52, v197, v199
	v_cvt_pk_bf16_f32 v53, v201, v203
	v_sub_f32_e32 v1, v26, v241
	s_waitcnt lgkmcnt(4)
	v_mfma_f32_32x32x16_bf16 v[2:17], v[108:111], v[116:119], v[2:17]
	v_exp_f32_e32 v187, v1
	v_sub_f32_e32 v1, v27, v241
	ds_read_b64_tr_b16 v[24:25], v211 offset:47616
	ds_read_b64_tr_b16 v[26:27], v211 offset:48768
	v_exp_f32_e32 v189, v1
	v_sub_f32_e32 v1, v28, v241
	v_exp_f32_e32 v205, v1
	v_sub_f32_e32 v1, v29, v241
	s_waitcnt lgkmcnt(4)
	v_mfma_f32_32x32x16_bf16 v[34:49], v[112:115], v[50:53], v[34:49]
	v_exp_f32_e32 v167, v1
	v_sub_f32_e32 v1, v30, v241
	v_sub_f32_e32 v19, v31, v241
	v_exp_f32_e32 v1, v1
	v_exp_f32_e32 v19, v19
	v_cvt_pk_bf16_f32 v28, v185, v191
	v_cvt_pk_bf16_f32 v29, v187, v189
	s_waitcnt lgkmcnt(2)
	v_mfma_f32_32x32x16_bf16 v[2:17], v[20:23], v[50:53], v[2:17]
	ds_read_b64_tr_b16 v[22:23], v211 offset:48832
	ds_read_b64_tr_b16 v[20:21], v211 offset:47680
	v_cvt_pk_bf16_f32 v50, v145, v149
	v_cvt_pk_bf16_f32 v51, v153, v157
	v_cvt_pk_bf16_f32 v52, v169, v171
	v_cvt_pk_bf16_f32 v53, v173, v179
	v_cvt_pk_bf16_f32 v30, v205, v167
	v_cvt_pk_bf16_f32 v31, v1, v19
	s_waitcnt lgkmcnt(2)
	v_mfma_f32_32x32x16_bf16 v[34:49], v[24:27], v[50:53], v[34:49]
	ds_read_b64_tr_b16 v[24:25], v211 offset:49920
	ds_read_b64_tr_b16 v[26:27], v211 offset:51072
	v_writelane_b32 v255, s11, 34
	s_waitcnt lgkmcnt(2)
	v_mfma_f32_32x32x16_bf16 v[2:17], v[20:23], v[50:53], v[2:17]
	ds_read_b64_tr_b16 v[22:23], v211 offset:51136
	ds_read_b64_tr_b16 v[20:21], v211 offset:49984
	s_waitcnt vmcnt(3)
	ds_write_b128 v207, v[66:69] offset:15360
	s_waitcnt vmcnt(2)
	ds_write_b128 v207, v[70:73] offset:24576
	s_waitcnt lgkmcnt(0)
	s_barrier
	v_mfma_f32_32x32x16_bf16 v[34:49], v[24:27], v[28:31], v[34:49]
	v_mfma_f32_32x32x16_bf16 v[2:17], v[20:23], v[28:31], v[2:17]
	ds_read_b128 v[20:23], v141 offset:15360
	ds_read_b128 v[24:27], v141 offset:15392
	v_add_f32_e32 v28, 0, v240
	s_waitcnt lgkmcnt(1)
	v_mfma_f32_32x32x16_bf16 v[52:67], v[20:23], v[92:95], 0
	ds_read_b128 v[20:23], v141 offset:15424
	s_waitcnt lgkmcnt(1)
	v_mfma_f32_32x32x16_bf16 v[52:67], v[24:27], v[88:91], v[52:67]
	ds_read_b128 v[24:27], v141 offset:15456
	s_waitcnt lgkmcnt(1)
	v_mfma_f32_32x32x16_bf16 v[52:67], v[20:23], v[84:87], v[52:67]
	v_add_f32_e32 v20, v239, v28
	v_mov_b32_e32 v21, v193
	v_add_f32_e64 v20, v82, v20
	v_add_f32_e64 v21, v83, v21
	v_add_f32_e64 v20, v146, v20
	v_add_f32_e64 v21, v147, v21
	v_pk_add_f32 v[20:21], v[150:151], v[20:21]
	s_waitcnt lgkmcnt(0)
	v_mfma_f32_32x32x16_bf16 v[52:67], v[24:27], v[96:99], v[52:67]
	v_add_f32_e64 v28, v154, v20
	v_add_f32_e64 v29, v155, v21
	ds_read_b128 v[20:23], v238 offset:15360
	v_add_f32_e64 v24, v144, v28
	v_add_f32_e64 v25, v145, v29
	v_pk_add_f32 v[24:25], v[148:149], v[24:25]
	s_nop 0
	v_pk_add_f32 v[24:25], v[152:153], v[24:25]
	s_nop 0
	v_pk_add_f32 v[24:25], v[156:157], v[24:25]
	s_nop 0
	v_pk_add_f32 v[24:25], v[160:161], v[24:25]
	s_nop 0
	v_pk_add_f32 v[28:29], v[162:163], v[24:25]
	ds_read_b128 v[24:27], v238 offset:15392
	s_waitcnt lgkmcnt(1)
	v_mfma_f32_32x32x16_bf16 v[68:83], v[20:23], v[92:95], 0
	v_add_f32_e64 v20, v158, v28
	v_add_f32_e64 v21, v159, v29
	v_add_f32_e64 v20, v164, v20
	v_add_f32_e64 v21, v165, v21
	v_add_f32_e64 v20, v168, v20
	v_add_f32_e64 v21, v169, v21
	v_pk_add_f32 v[20:21], v[170:171], v[20:21]
	s_waitcnt lgkmcnt(0)
	v_mfma_f32_32x32x16_bf16 v[68:83], v[24:27], v[88:91], v[68:83]
	v_add_f32_e64 v20, v172, v20
	v_add_f32_e64 v21, v173, v21
	v_add_f32_e64 v28, v178, v20
	v_add_f32_e64 v29, v179, v21
	ds_read_b128 v[20:23], v238 offset:15424
	v_pk_add_f32 v[24:25], v[174:175], v[28:29]
	v_mov_b32_e32 v175, v193
	v_pk_add_f32 v[24:25], v[176:177], v[24:25]
	s_nop 0
	v_pk_add_f32 v[24:25], v[180:181], v[24:25]
	s_nop 0
	v_pk_add_f32 v[24:25], v[182:183], v[24:25]
	s_nop 0
	v_pk_add_f32 v[24:25], v[184:185], v[24:25]
	s_nop 0
	v_pk_add_f32 v[28:29], v[190:191], v[24:25]
	ds_read_b128 v[24:27], v238 offset:15456
	s_waitcnt lgkmcnt(1)
	v_mfma_f32_32x32x16_bf16 v[68:83], v[20:23], v[84:87], v[68:83]
	v_add_f32_e64 v20, v186, v28
	v_add_f32_e64 v21, v187, v29
	v_add_f32_e64 v20, v188, v20
	v_add_f32_e64 v21, v189, v21
	v_add_f32_e64 v20, v196, v20
	v_add_f32_e64 v21, v197, v21
	v_pk_add_f32 v[20:21], v[198:199], v[20:21]
	s_waitcnt lgkmcnt(0)
	v_mfma_f32_32x32x16_bf16 v[68:83], v[24:27], v[96:99], v[68:83]
	v_max_f32_e32 v25, v54, v54
	v_add_f32_e64 v20, v200, v20
	v_add_f32_e64 v21, v201, v21
	v_add_f32_e64 v20, v202, v20
	v_add_f32_e64 v21, v203, v21
	v_pk_add_f32 v[20:21], v[204:205], v[20:21]
	s_nop 5
	v_max_f32_e32 v22, v69, v69
	v_max_f32_e32 v23, v68, v68
	v_max_f32_e32 v22, v23, v22
	v_max_f32_e32 v23, v71, v71
	v_max_f32_e32 v24, v70, v70
	v_max_f32_e32 v23, v24, v23
	v_max3_f32 v22, v22, s23, v23
	v_max_f32_e32 v23, v53, v53
	v_max_f32_e32 v24, v52, v52
	v_max_f32_e32 v23, v24, v23
	v_max_f32_e32 v24, v55, v55
	v_max_f32_e32 v24, v25, v24
	v_max3_f32 v22, v22, v23, v24
	v_max_f32_e32 v23, v73, v73
	v_max_f32_e32 v24, v72, v72
	v_max_f32_e32 v23, v24, v23
	v_max_f32_e32 v24, v75, v75
	v_max_f32_e32 v25, v74, v74
	v_max_f32_e32 v24, v25, v24
	v_max3_f32 v22, v22, v23, v24
	v_max_f32_e32 v23, v57, v57
	v_max_f32_e32 v24, v56, v56
	v_max_f32_e32 v23, v24, v23
	v_max_f32_e32 v24, v59, v59
	v_max_f32_e32 v25, v58, v58
	v_max_f32_e32 v24, v25, v24
	v_max3_f32 v22, v22, v23, v24
	v_max_f32_e32 v23, v77, v77
	v_max_f32_e32 v24, v76, v76
	v_max_f32_e32 v23, v24, v23
	v_max_f32_e32 v24, v79, v79
	v_max_f32_e32 v25, v78, v78
	v_max_f32_e32 v24, v25, v24
	v_max3_f32 v22, v22, v23, v24
	v_max_f32_e32 v23, v61, v61
	v_max_f32_e32 v24, v60, v60
	v_max_f32_e32 v23, v24, v23
	v_max_f32_e32 v24, v63, v63
	v_max_f32_e32 v25, v62, v62
	v_max_f32_e32 v24, v25, v24
	v_max3_f32 v22, v22, v23, v24
	v_max_f32_e32 v23, v81, v81
	v_max_f32_e32 v24, v80, v80
	v_max_f32_e32 v23, v24, v23
	v_max_f32_e32 v24, v83, v83
	v_max_f32_e32 v25, v82, v82
	v_max_f32_e32 v24, v25, v24
	v_max3_f32 v22, v22, v23, v24
	v_max_f32_e32 v23, v65, v65
	v_max_f32_e32 v24, v64, v64
	v_max_f32_e32 v23, v24, v23
	v_max_f32_e32 v24, v67, v67
	v_max_f32_e32 v25, v66, v66
	v_max_f32_e32 v24, v25, v24
	v_max3_f32 v22, v22, v23, v24
	ds_bpermute_b32 v23, v210, v22
	v_pk_add_f32 v[20:21], v[166:167], v[20:21]
	s_waitcnt lgkmcnt(0)
	v_max3_f32 v125, v241, v22, v23
	v_pk_add_f32 v[0:1], v[0:1], v[20:21]
	v_sub_f32_e32 v22, v58, v125
	v_add_f32_e32 v1, v1, v19
	v_sub_f32_e32 v19, v68, v125
	v_fmac_f32_e32 v1, v0, v18
	v_sub_f32_e32 v18, v55, v125
	v_exp_f32_e32 v127, v19
	v_sub_f32_e32 v19, v69, v125
	v_exp_f32_e32 v124, v18
	v_sub_f32_e32 v18, v72, v125
	v_exp_f32_e32 v129, v19
	v_exp_f32_e32 v126, v18
	v_sub_f32_e32 v18, v73, v125
	v_exp_f32_e32 v128, v18
	v_sub_f32_e32 v18, v74, v125
	v_exp_f32_e32 v154, v18
	v_sub_f32_e32 v18, v75, v125
	v_add_f32_e32 v0, 0, v127
	v_exp_f32_e32 v156, v18
	v_sub_f32_e32 v18, v56, v125
	v_add_f32_e32 v174, v129, v0
	v_sub_f32_e32 v0, v70, v125
	v_exp_f32_e32 v130, v18
	v_sub_f32_e32 v18, v57, v125
	v_exp_f32_e32 v146, v0
	v_sub_f32_e32 v0, v71, v125
	v_exp_f32_e32 v144, v18
	ds_read_b64_tr_b16 v[176:177], v211 offset:24576
	ds_read_b64_tr_b16 v[178:179], v211 offset:25728
	ds_read_b64_tr_b16 v[182:183], v211 offset:25792
	ds_read_b64_tr_b16 v[180:181], v211 offset:24640
	ds_read_b64_tr_b16 v[120:121], v211 offset:26880
	ds_read_b64_tr_b16 v[122:123], v211 offset:28032
	ds_read_b64_tr_b16 v[114:115], v211 offset:28096
	ds_read_b64_tr_b16 v[112:113], v211 offset:26944
	ds_read_b64_tr_b16 v[116:117], v211 offset:29184
	ds_read_b64_tr_b16 v[118:119], v211 offset:30336
	ds_read_b64_tr_b16 v[110:111], v211 offset:30400
	ds_read_b64_tr_b16 v[108:109], v211 offset:29248
	ds_read_b64_tr_b16 v[72:73], v211 offset:31488
	ds_read_b64_tr_b16 v[74:75], v211 offset:32640
	ds_read_b64_tr_b16 v[70:71], v211 offset:32704
	ds_read_b64_tr_b16 v[68:69], v211 offset:31552
	s_waitcnt vmcnt(1)
	ds_write_b128 v207, v[100:103] offset:33792
	s_waitcnt vmcnt(0)
	ds_write_b128 v207, v[104:107] offset:43008
	s_waitcnt lgkmcnt(0)
	s_barrier
	ds_read_b128 v[18:21], v141 offset:33792
	v_exp_f32_e32 v100, v22
	v_sub_f32_e32 v22, v59, v125
	v_exp_f32_e32 v148, v0
	v_sub_f32_e32 v0, v52, v125
	v_exp_f32_e32 v102, v22
	v_sub_f32_e32 v22, v76, v125
	v_exp_f32_e32 v150, v0
	v_sub_f32_e32 v0, v53, v125
	v_exp_f32_e32 v76, v22
	v_sub_f32_e32 v22, v77, v125
	ds_read_b128 v[50:53], v141 offset:33824
	v_exp_f32_e32 v104, v22
	s_waitcnt lgkmcnt(1)
	v_mfma_f32_32x32x16_bf16 v[18:33], v[18:21], v[92:95], 0
	v_exp_f32_e32 v152, v0
	v_sub_f32_e32 v0, v54, v125
	v_sub_f32_e32 v54, v78, v125
	v_exp_f32_e32 v160, v54
	v_sub_f32_e32 v54, v79, v125
	v_exp_f32_e32 v164, v54
	v_sub_f32_e32 v54, v60, v125
	v_exp_f32_e32 v168, v54
	ds_read_b128 v[54:57], v141 offset:33856
	s_waitcnt lgkmcnt(1)
	v_mfma_f32_32x32x16_bf16 v[18:33], v[50:53], v[88:91], v[18:33]
	v_sub_f32_e32 v50, v61, v125
	v_exp_f32_e32 v172, v50
	v_sub_f32_e32 v50, v62, v125
	v_exp_f32_e32 v78, v50
	v_sub_f32_e32 v50, v63, v125
	v_exp_f32_e32 v106, v50
	ds_read_b128 v[50:53], v141 offset:33888
	s_waitcnt lgkmcnt(1)
	v_mfma_f32_32x32x16_bf16 v[18:33], v[54:57], v[84:87], v[18:33]
	v_sub_f32_e32 v54, v80, v125
	v_exp_f32_e32 v80, v54
	v_sub_f32_e32 v54, v81, v125
	v_exp_f32_e32 v158, v54
	v_sub_f32_e32 v54, v82, v125
	v_exp_f32_e32 v82, v54
	ds_read_b128 v[54:57], v238 offset:33792
	ds_read_b128 v[184:187], v238 offset:33824
	s_waitcnt lgkmcnt(2)
	v_mfma_f32_32x32x16_bf16 v[18:33], v[50:53], v[96:99], v[18:33]
	v_sub_f32_e32 v50, v83, v125
	v_exp_f32_e32 v162, v50
	v_sub_f32_e32 v50, v64, v125
	v_exp_f32_e32 v166, v50
	v_sub_f32_e32 v50, v65, v125
	v_exp_f32_e32 v170, v50
	ds_read_b128 v[188:191], v238 offset:33856
	s_waitcnt lgkmcnt(2)
	v_mfma_f32_32x32x16_bf16 v[50:65], v[54:57], v[92:95], 0
	v_sub_f32_e32 v131, v241, v125
	v_exp_f32_e32 v196, v131
	v_sub_f32_e32 v67, v67, v125
	v_exp_f32_e32 v94, v67
	v_max_f32_e32 v79, v20, v20
	v_mul_f32_e32 v92, v1, v196
	v_pk_mul_f32 v[48:49], v[48:49], v[196:197] op_sel_hi:[1,0]
	s_waitcnt lgkmcnt(1)
	v_mfma_f32_32x32x16_bf16 v[50:65], v[184:187], v[88:91], v[50:65]
	ds_read_b128 v[88:91], v238 offset:33888
	v_mul_f32_e64 v46, v46, v196
	v_mul_f32_e64 v47, v47, v196
	v_mul_f32_e64 v44, v44, v196
	v_mul_f32_e64 v45, v45, v196
	v_pk_mul_f32 v[42:43], v[42:43], v[196:197] op_sel_hi:[1,0]
	v_pk_mul_f32 v[40:41], v[40:41], v[196:197] op_sel_hi:[1,0]
	v_pk_mul_f32 v[38:39], v[38:39], v[196:197] op_sel_hi:[1,0]
	v_pk_mul_f32 v[36:37], v[36:37], v[196:197] op_sel_hi:[1,0]
	s_waitcnt lgkmcnt(1)
	v_mfma_f32_32x32x16_bf16 v[50:65], v[188:191], v[84:87], v[50:65]
	v_mul_f32_e64 v34, v34, v196
	v_mul_f32_e64 v35, v35, v196
	v_mul_f32_e64 v16, v16, v196
	v_mul_f32_e64 v17, v17, v196
	v_mul_f32_e64 v14, v14, v196
	v_mul_f32_e64 v15, v15, v196
	v_pk_mul_f32 v[12:13], v[12:13], v[196:197] op_sel_hi:[1,0]
	v_pk_mul_f32 v[10:11], v[10:11], v[196:197] op_sel_hi:[1,0]
	v_pk_mul_f32 v[8:9], v[8:9], v[196:197] op_sel_hi:[1,0]
	v_pk_mul_f32 v[6:7], v[6:7], v[196:197] op_sel_hi:[1,0]
	s_waitcnt lgkmcnt(0)
	v_mfma_f32_32x32x16_bf16 v[50:65], v[88:91], v[96:99], v[50:65]
	v_mul_f32_e64 v4, v4, v196
	v_mul_f32_e64 v5, v5, v196
	v_mul_f32_e64 v2, v2, v196
	v_mul_f32_e64 v3, v3, v196
	v_cvt_pk_bf16_f32 v84, v127, v129
	v_cvt_pk_bf16_f32 v85, v146, v148
	v_cvt_pk_bf16_f32 v86, v126, v128
	v_cvt_pk_bf16_f32 v87, v154, v156
	v_sub_f32_e32 v66, v66, v125
	s_nop 2
	v_max_f32_e32 v1, v51, v51
	v_max_f32_e32 v67, v50, v50
	v_max_f32_e32 v1, v67, v1
	v_max_f32_e32 v67, v53, v53
	v_max_f32_e32 v77, v52, v52
	v_max_f32_e32 v67, v77, v67
	v_max3_f32 v1, v1, s23, v67
	v_max_f32_e32 v67, v19, v19
	v_max_f32_e32 v77, v18, v18
	v_max_f32_e32 v67, v77, v67
	v_max_f32_e32 v77, v21, v21
	v_max_f32_e32 v77, v79, v77
	v_max3_f32 v1, v1, v67, v77
	v_max_f32_e32 v67, v55, v55
	v_max_f32_e32 v77, v54, v54
	v_max_f32_e32 v67, v77, v67
	v_max_f32_e32 v77, v57, v57
	v_max_f32_e32 v79, v56, v56
	v_max_f32_e32 v77, v79, v77
	v_max3_f32 v1, v1, v67, v77
	v_max_f32_e32 v67, v23, v23
	v_max_f32_e32 v77, v22, v22
	v_max_f32_e32 v67, v77, v67
	v_max_f32_e32 v77, v25, v25
	v_max_f32_e32 v79, v24, v24
	v_max_f32_e32 v77, v79, v77
	v_max3_f32 v1, v1, v67, v77
	v_max_f32_e32 v67, v59, v59
	v_max_f32_e32 v77, v58, v58
	v_max_f32_e32 v67, v77, v67
	v_max_f32_e32 v77, v61, v61
	v_max_f32_e32 v79, v60, v60
	v_max_f32_e32 v77, v79, v77
	v_max3_f32 v1, v1, v67, v77
	v_max_f32_e32 v67, v27, v27
	v_max_f32_e32 v77, v26, v26
	v_max_f32_e32 v67, v77, v67
	v_max_f32_e32 v77, v29, v29
	v_max_f32_e32 v79, v28, v28
	v_max_f32_e32 v77, v79, v77
	v_max3_f32 v1, v1, v67, v77
	v_max_f32_e32 v67, v63, v63
	v_max_f32_e32 v77, v62, v62
	v_max_f32_e32 v67, v77, v67
	v_max_f32_e32 v77, v65, v65
	v_max_f32_e32 v79, v64, v64
	v_max_f32_e32 v77, v79, v77
	v_max3_f32 v1, v1, v67, v77
	v_max_f32_e32 v67, v31, v31
	v_max_f32_e32 v77, v30, v30
	v_max_f32_e32 v67, v77, v67
	v_max_f32_e32 v77, v33, v33
	v_max_f32_e32 v79, v32, v32
	v_max_f32_e32 v77, v79, v77
	v_max3_f32 v1, v1, v67, v77
	ds_bpermute_b32 v67, v210, v1
	v_mfma_f32_32x32x16_bf16 v[34:49], v[176:179], v[84:87], v[34:49]
	v_exp_f32_e32 v0, v0
	v_exp_f32_e32 v66, v66
	v_mov_b32_e32 v141, v193
	s_waitcnt lgkmcnt(0)
	v_max3_f32 v96, v125, v1, v67
	v_sub_f32_e32 v1, v50, v96
	v_exp_f32_e32 v147, v1
	v_sub_f32_e32 v1, v51, v96
	v_mfma_f32_32x32x16_bf16 v[2:17], v[180:183], v[84:87], v[2:17]
	v_exp_f32_e32 v149, v1
	v_sub_f32_e32 v1, v52, v96
	v_exp_f32_e32 v151, v1
	v_sub_f32_e32 v1, v53, v96
	v_exp_f32_e32 v153, v1
	v_sub_f32_e32 v1, v18, v96
	v_sub_f32_e32 v18, v19, v96
	v_sub_f32_e32 v67, v125, v96
	v_exp_f32_e32 v125, v18
	v_sub_f32_e32 v18, v20, v96
	v_exp_f32_e32 v127, v18
	v_sub_f32_e32 v18, v21, v96
	v_exp_f32_e32 v129, v18
	v_sub_f32_e32 v18, v54, v96
	v_exp_f32_e32 v1, v1
	v_exp_f32_e32 v155, v18
	v_pk_add_f32 v[18:19], v[146:147], v[174:175]
	v_cvt_pk_bf16_f32 v50, v76, v104
	v_cvt_pk_bf16_f32 v51, v160, v164
	v_cvt_pk_bf16_f32 v52, v80, v158
	v_cvt_pk_bf16_f32 v53, v82, v162
	v_pk_add_f32 v[18:19], v[148:149], v[18:19]
	v_cvt_pk_bf16_f32 v21, v0, v124
	v_mfma_f32_32x32x16_bf16 v[34:49], v[120:123], v[50:53], v[34:49]
	v_add_f32_e64 v18, v150, v18
	v_add_f32_e64 v19, v151, v19
	v_cvt_pk_bf16_f32 v20, v150, v152
	v_add_f32_e64 v18, v152, v18
	v_add_f32_e64 v19, v153, v19
	v_pk_add_f32 v[18:19], v[0:1], v[18:19]
	v_sub_f32_e32 v0, v55, v96
	v_exp_f32_e32 v157, v0
	v_mfma_f32_32x32x16_bf16 v[2:17], v[112:115], v[50:53], v[2:17]
	v_sub_f32_e32 v0, v56, v96
	v_exp_f32_e32 v131, v0
	v_sub_f32_e32 v0, v57, v96
	v_exp_f32_e32 v145, v0
	v_sub_f32_e32 v0, v22, v96
	v_exp_f32_e32 v101, v0
	v_sub_f32_e32 v0, v23, v96
	v_cvt_pk_bf16_f32 v22, v130, v144
	v_cvt_pk_bf16_f32 v23, v100, v102
	v_exp_f32_e32 v103, v0
	v_sub_f32_e32 v0, v24, v96
	v_mfma_f32_32x32x16_bf16 v[34:49], v[116:119], v[20:23], v[34:49]
	v_exp_f32_e32 v77, v0
	v_sub_f32_e32 v0, v25, v96
	v_exp_f32_e32 v105, v0
	v_sub_f32_e32 v0, v58, v96
	v_exp_f32_e32 v161, v0
	v_sub_f32_e32 v0, v59, v96
	v_exp_f32_e32 v165, v0
	v_mfma_f32_32x32x16_bf16 v[2:17], v[108:111], v[20:23], v[2:17]
	v_sub_f32_e32 v0, v60, v96
	v_exp_f32_e32 v169, v0
	v_sub_f32_e32 v0, v61, v96
	v_exp_f32_e32 v173, v0
	v_sub_f32_e32 v0, v26, v96
	v_cvt_pk_bf16_f32 v24, v168, v172
	v_exp_f32_e32 v79, v0
	v_sub_f32_e32 v0, v27, v96
	v_cvt_pk_bf16_f32 v25, v78, v106
	v_cvt_pk_bf16_f32 v26, v166, v170
	v_cvt_pk_bf16_f32 v27, v66, v94
	v_exp_f32_e32 v107, v0
	v_sub_f32_e32 v0, v28, v96
	v_mfma_f32_32x32x16_bf16 v[34:49], v[72:75], v[24:27], v[34:49]
	v_exp_f32_e32 v81, v0
	v_sub_f32_e32 v0, v29, v96
	v_pk_add_f32 v[18:19], v[124:125], v[18:19]
	v_exp_f32_e32 v159, v0
	v_sub_f32_e32 v0, v62, v96
	v_pk_add_f32 v[18:19], v[126:127], v[18:19]
	v_exp_f32_e32 v83, v0
	v_mfma_f32_32x32x16_bf16 v[2:17], v[68:71], v[24:27], v[2:17]
	v_sub_f32_e32 v0, v63, v96
	v_sub_f32_e32 v20, v64, v96
	v_add_f32_e64 v18, v128, v18
	v_add_f32_e64 v19, v129, v19
	v_exp_f32_e32 v163, v0
	v_exp_f32_e32 v0, v67
	v_exp_f32_e32 v167, v20
	ds_read_b64_tr_b16 v[20:21], v211 offset:43008
	ds_read_b64_tr_b16 v[22:23], v211 offset:44160
	ds_read_b64_tr_b16 v[26:27], v211 offset:44224
	ds_read_b64_tr_b16 v[24:25], v211 offset:43072
	v_lshlrev_b64 v[28:29], 11, v[142:143]
	v_pk_add_f32 v[18:19], v[154:155], v[18:19]
	v_lshl_add_u64 v[28:29], s[0:1], 0, v[28:29]
	v_pk_add_f32 v[18:19], v[156:157], v[18:19]
	v_lshl_add_u64 v[28:29], v[28:29], 0, s[18:19]
	v_pk_add_f32 v[18:19], v[130:131], v[18:19]
	v_lshl_add_u64 v[28:29], v[28:29], 0, v[140:141]
	v_pk_add_f32 v[18:19], v[144:145], v[18:19]
	v_pk_mul_f32 v[48:49], v[48:49], v[0:1] op_sel_hi:[1,0]
	v_pk_mul_f32 v[46:47], v[46:47], v[0:1] op_sel_hi:[1,0]
	v_pk_mul_f32 v[44:45], v[44:45], v[0:1] op_sel_hi:[1,0]
	v_pk_mul_f32 v[42:43], v[42:43], v[0:1] op_sel_hi:[1,0]
	v_pk_mul_f32 v[40:41], v[40:41], v[0:1] op_sel_hi:[1,0]
	v_pk_mul_f32 v[38:39], v[38:39], v[0:1] op_sel_hi:[1,0]
	v_pk_mul_f32 v[36:37], v[36:37], v[0:1] op_sel_hi:[1,0]
	v_pk_mul_f32 v[34:35], v[34:35], v[0:1] op_sel_hi:[1,0]
	v_pk_mul_f32 v[16:17], v[16:17], v[0:1] op_sel_hi:[1,0]
	v_cvt_pk_bf16_f32 v50, v147, v149
	v_cvt_pk_bf16_f32 v51, v151, v153
	v_cvt_pk_bf16_f32 v52, v155, v157
	ds_read_b64_tr_b16 v[54:55], v211 offset:45312
	ds_read_b64_tr_b16 v[56:57], v211 offset:46464
	ds_read_b64_tr_b16 v[60:61], v211 offset:46528
	ds_read_b64_tr_b16 v[58:59], v211 offset:45376
	ds_read_b64_tr_b16 v[68:69], v211 offset:47616
	ds_read_b64_tr_b16 v[70:71], v211 offset:48768
	ds_read_b64_tr_b16 v[74:75], v211 offset:48832
	ds_read_b64_tr_b16 v[72:73], v211 offset:47680
	ds_read_b64_tr_b16 v[84:85], v211 offset:49920
	ds_read_b64_tr_b16 v[86:87], v211 offset:51072
	ds_read_b64_tr_b16 v[90:91], v211 offset:51136
	ds_read_b64_tr_b16 v[88:89], v211 offset:49984
	s_waitcnt lgkmcnt(0)
	s_barrier
	v_mov_b64_e32 v[62:63], v[224:225]
	v_cvt_pk_bf16_f32 v53, v131, v145
	v_pk_mul_f32 v[14:15], v[14:15], v[0:1] op_sel_hi:[1,0]
	v_pk_mul_f32 v[12:13], v[12:13], v[0:1] op_sel_hi:[1,0]
	v_pk_mul_f32 v[10:11], v[10:11], v[0:1] op_sel_hi:[1,0]
	v_pk_mul_f32 v[8:9], v[8:9], v[0:1] op_sel_hi:[1,0]
	v_pk_mul_f32 v[6:7], v[6:7], v[0:1] op_sel_hi:[1,0]
	v_pk_mul_f32 v[4:5], v[4:5], v[0:1] op_sel_hi:[1,0]
	v_pk_mul_f32 v[2:3], v[2:3], v[0:1] op_sel_hi:[1,0]
	v_pk_add_f32 v[18:19], v[100:101], v[18:19]
	v_mfma_f32_32x32x16_bf16 v[34:49], v[20:23], v[50:53], v[34:49]
	v_add_f32_e64 v18, v102, v18
	v_add_f32_e64 v19, v103, v19
	v_sub_f32_e32 v20, v65, v96
	v_add_f32_e64 v18, v76, v18
	v_add_f32_e64 v19, v77, v19
	v_exp_f32_e32 v171, v20
	v_pk_add_f32 v[18:19], v[104:105], v[18:19]
	v_cvt_pk_bf16_f32 v20, v161, v165
	v_pk_add_f32 v[18:19], v[160:161], v[18:19]
	v_mfma_f32_32x32x16_bf16 v[2:17], v[24:27], v[50:53], v[2:17]
	v_mov_b64_e32 v[24:25], v[226:227]
	v_add_f32_e64 v18, v164, v18
	v_add_f32_e64 v19, v165, v19
	v_sub_f32_e32 v26, v30, v96
	v_add_f32_e64 v18, v168, v18
	v_add_f32_e64 v19, v169, v19
	v_cvt_pk_bf16_f32 v21, v169, v173
	v_pk_add_f32 v[18:19], v[172:173], v[18:19]
	v_cvt_pk_bf16_f32 v22, v83, v163
	v_cvt_pk_bf16_f32 v23, v167, v171
	v_exp_f32_e32 v67, v26
	v_mov_b64_e32 v[26:27], v[246:247]
	v_mfma_f32_32x32x16_bf16 v[34:49], v[54:57], v[20:23], v[34:49]
	v_sub_f32_e32 v30, v31, v96
	v_exp_f32_e32 v95, v30
	v_sub_f32_e32 v30, v32, v96
	v_exp_f32_e32 v93, v30
	v_sub_f32_e32 v30, v33, v96
	v_exp_f32_e32 v50, v30
	v_mov_b64_e32 v[30:31], v[248:249]
	v_mfma_f32_32x32x16_bf16 v[2:17], v[58:61], v[20:23], v[2:17]
	v_add_f32_e64 v22, v78, v18
	v_add_f32_e64 v23, v79, v19
	v_cvt_pk_bf16_f32 v18, v1, v125
	v_add_f32_e64 v22, v106, v22
	v_add_f32_e64 v23, v107, v23
	v_cvt_pk_bf16_f32 v19, v127, v129
	v_pk_add_f32 v[22:23], v[80:81], v[22:23]
	v_cvt_pk_bf16_f32 v20, v101, v103
	v_pk_add_f32 v[22:23], v[158:159], v[22:23]
	v_cvt_pk_bf16_f32 v21, v77, v105
	v_pk_add_f32 v[22:23], v[82:83], v[22:23]
	v_mov_b64_e32 v[32:33], v[214:215]
	v_pk_add_f32 v[22:23], v[162:163], v[22:23]
	v_mfma_f32_32x32x16_bf16 v[34:49], v[68:71], v[18:21], v[34:49]
	v_add_f32_e64 v22, v166, v22
	v_add_f32_e64 v23, v167, v23
	v_add_f32_e64 v22, v170, v22
	v_add_f32_e64 v23, v171, v23
	v_mfma_f32_32x32x16_bf16 v[2:17], v[72:75], v[18:21], v[2:17]
	v_add_f32_e64 v18, v66, v22
	v_add_f32_e64 v19, v67, v23
	v_cvt_pk_bf16_f32 v20, v67, v95
	v_add_f32_e64 v18, v94, v18
	v_add_f32_e64 v19, v95, v19
	v_cvt_pk_bf16_f32 v21, v93, v50
	v_pk_add_f32 v[22:23], v[92:93], v[18:19]
	v_cvt_pk_bf16_f32 v18, v79, v107
	v_add_f32_e32 v23, v23, v50
	v_fmac_f32_e32 v23, v22, v0
	v_mov_b64_e32 v[0:1], v[216:217]
	v_cvt_pk_bf16_f32 v19, v81, v159
	ds_bpermute_b32 v22, v210, v23
	s_waitcnt lgkmcnt(0)
	v_add_f32_e32 v22, v23, v22
	v_mfma_f32_32x32x16_bf16 v[34:49], v[84:87], v[18:21], v[34:49]
	v_div_scale_f32 v23, s[10:11], v22, v22, 1.0
	v_rcp_f32_e32 v50, v23
	v_readlane_b32 s10, v254, 56
	v_readlane_b32 s11, v254, 57
	v_fma_f32 v51, -v23, v50, 1.0
	v_mfma_f32_32x32x16_bf16 v[2:17], v[88:91], v[18:21], v[2:17]
	v_mov_b64_e32 v[18:19], v[230:231]
	v_mov_b64_e32 v[20:21], v[232:233]
	v_fmac_f32_e32 v50, v51, v50
	v_div_scale_f32 v51, vcc, 1.0, v22, 1.0
	v_mul_f32_e32 v52, v51, v50
	v_fma_f32 v53, -v23, v52, v51
	v_fmac_f32_e32 v52, v53, v50
	v_fma_f32 v23, -v23, v52, v51
	v_div_fmas_f32 v23, v23, v50, v52
	v_div_fixup_f32 v22, v23, v22, 1.0
	v_pk_mul_f32 v[34:35], v[34:35], v[22:23] op_sel_hi:[1,0]
	s_waitcnt vmcnt(7)
	v_lshlrev_b32_e32 v50, 16, v62
	v_and_b32_e32 v51, 0xffff0000, v62
	v_pk_mul_f32 v[34:35], v[34:35], v[50:51]
	v_pk_mul_f32 v[36:37], v[36:37], v[22:23] op_sel_hi:[1,0]
	v_lshlrev_b32_e32 v50, 16, v63
	v_and_b32_e32 v51, 0xffff0000, v63
	v_pk_mul_f32 v[36:37], v[36:37], v[50:51]
	v_cvt_pk_bf16_f32 v34, v34, v35
	v_cvt_pk_bf16_f32 v35, v36, v37
	global_store_dwordx2 v[28:29], v[34:35], off
	v_pk_mul_f32 v[34:35], v[38:39], v[22:23] op_sel_hi:[1,0]
	s_waitcnt vmcnt(7)
	v_lshlrev_b32_e32 v36, 16, v24
	v_and_b32_e32 v37, 0xffff0000, v24
	v_pk_mul_f32 v[34:35], v[34:35], v[36:37]
	v_lshlrev_b32_e32 v36, 16, v25
	v_cvt_pk_bf16_f32 v24, v34, v35
	v_pk_mul_f32 v[34:35], v[40:41], v[22:23] op_sel_hi:[1,0]
	v_and_b32_e32 v37, 0xffff0000, v25
	v_pk_mul_f32 v[34:35], v[34:35], v[36:37]
	v_pk_mul_f32 v[2:3], v[2:3], v[22:23] op_sel_hi:[1,0]
	v_cvt_pk_bf16_f32 v25, v34, v35
	global_store_dwordx2 v[28:29], v[24:25], off offset:16
	v_pk_mul_f32 v[24:25], v[42:43], v[22:23] op_sel_hi:[1,0]
	s_waitcnt vmcnt(7)
	v_lshlrev_b32_e32 v34, 16, v26
	v_and_b32_e32 v35, 0xffff0000, v26
	v_pk_mul_f32 v[24:25], v[24:25], v[34:35]
	v_pk_mul_f32 v[34:35], v[44:45], v[22:23] op_sel_hi:[1,0]
	v_lshlrev_b32_e32 v26, 16, v27
	v_and_b32_e32 v27, 0xffff0000, v27
	v_pk_mul_f32 v[26:27], v[34:35], v[26:27]
	v_cvt_pk_bf16_f32 v24, v24, v25
	v_cvt_pk_bf16_f32 v25, v26, v27
	global_store_dwordx2 v[28:29], v[24:25], off offset:32
	v_pk_mul_f32 v[24:25], v[46:47], v[22:23] op_sel_hi:[1,0]
	s_waitcnt vmcnt(7)
	v_lshlrev_b32_e32 v26, 16, v30
	v_and_b32_e32 v27, 0xffff0000, v30
	v_pk_mul_f32 v[24:25], v[24:25], v[26:27]
	v_pk_mul_f32 v[26:27], v[48:49], v[22:23] op_sel_hi:[1,0]
	v_lshlrev_b32_e32 v30, 16, v31
	v_and_b32_e32 v31, 0xffff0000, v31
	v_pk_mul_f32 v[26:27], v[26:27], v[30:31]
	v_cvt_pk_bf16_f32 v24, v24, v25
	v_cvt_pk_bf16_f32 v25, v26, v27
	global_store_dwordx2 v[28:29], v[24:25], off offset:48
	s_waitcnt vmcnt(7)
	v_lshlrev_b32_e32 v24, 16, v32
	v_and_b32_e32 v25, 0xffff0000, v32
	v_pk_mul_f32 v[2:3], v[2:3], v[24:25]
	v_pk_mul_f32 v[4:5], v[4:5], v[22:23] op_sel_hi:[1,0]
	v_lshlrev_b32_e32 v24, 16, v33
	v_and_b32_e32 v25, 0xffff0000, v33
	v_pk_mul_f32 v[4:5], v[4:5], v[24:25]
	v_cvt_pk_bf16_f32 v2, v2, v3
	v_cvt_pk_bf16_f32 v3, v4, v5
	global_store_dwordx2 v[28:29], v[2:3], off offset:64
	v_pk_mul_f32 v[2:3], v[6:7], v[22:23] op_sel_hi:[1,0]
	s_waitcnt vmcnt(7)
	v_lshlrev_b32_e32 v4, 16, v0
	v_and_b32_e32 v5, 0xffff0000, v0
	v_pk_mul_f32 v[2:3], v[2:3], v[4:5]
	v_lshlrev_b32_e32 v4, 16, v1
	v_cvt_pk_bf16_f32 v0, v2, v3
	v_pk_mul_f32 v[2:3], v[8:9], v[22:23] op_sel_hi:[1,0]
	v_and_b32_e32 v5, 0xffff0000, v1
	v_pk_mul_f32 v[2:3], v[2:3], v[4:5]
	s_andn2_b64 vcc, exec, s[10:11]
	v_cvt_pk_bf16_f32 v1, v2, v3
	global_store_dwordx2 v[28:29], v[0:1], off offset:80
	v_pk_mul_f32 v[0:1], v[10:11], v[22:23] op_sel_hi:[1,0]
	s_waitcnt vmcnt(7)
	v_lshlrev_b32_e32 v2, 16, v18
	v_and_b32_e32 v3, 0xffff0000, v18
	v_pk_mul_f32 v[0:1], v[0:1], v[2:3]
	v_pk_mul_f32 v[2:3], v[12:13], v[22:23] op_sel_hi:[1,0]
	v_lshlrev_b32_e32 v4, 16, v19
	v_and_b32_e32 v5, 0xffff0000, v19
	v_pk_mul_f32 v[2:3], v[2:3], v[4:5]
	v_cvt_pk_bf16_f32 v0, v0, v1
	v_cvt_pk_bf16_f32 v1, v2, v3
	global_store_dwordx2 v[28:29], v[0:1], off offset:96
	v_pk_mul_f32 v[0:1], v[14:15], v[22:23] op_sel_hi:[1,0]
	s_waitcnt vmcnt(7)
	v_lshlrev_b32_e32 v2, 16, v20
	v_and_b32_e32 v3, 0xffff0000, v20
	v_pk_mul_f32 v[0:1], v[0:1], v[2:3]
	v_pk_mul_f32 v[2:3], v[16:17], v[22:23] op_sel_hi:[1,0]
	v_lshlrev_b32_e32 v4, 16, v21
	v_and_b32_e32 v5, 0xffff0000, v21
	v_pk_mul_f32 v[2:3], v[2:3], v[4:5]
	v_cvt_pk_bf16_f32 v0, v0, v1
	v_cvt_pk_bf16_f32 v1, v2, v3
	global_store_dwordx2 v[28:29], v[0:1], off offset:112
	s_cbranch_vccnz .LBB0_1405
	v_readlane_b32 s5, v254, 58
	s_add_i32 s4, s4, s5
	v_lshlrev_b64 v[0:1], 9, v[132:133]
	v_or_b32_e32 v132, s4, v135
	v_readlane_b32 s10, v255, 21
	v_ashrrev_i32_e32 v133, 31, v132
	v_readlane_b32 s16, v255, 35
	s_add_u32 s4, s50, s10
	v_lshlrev_b64 v[2:3], 10, v[132:133]
	v_readlane_b32 s17, v255, 36
	s_addc_u32 s5, s51, 0
	v_lshl_add_u64 v[2:3], s[20:21], 0, v[2:3]
	s_mov_b32 s17, s13
	v_lshlrev_b64 v[204:205], 11, v[132:133]
	v_lshlrev_b32_e32 v224, 1, v206
	v_mov_b32_e32 v225, 0
	v_lshl_add_u64 v[204:205], s[0:1], 0, v[204:205]
	v_lshl_add_u64 v[204:205], v[204:205], 0, s[16:17]
	v_lshl_add_u64 v[204:205], v[204:205], 0, v[224:225]
	global_load_dwordx2 v[238:239], v[204:205], off
	global_load_dwordx2 v[240:241], v[204:205], off offset:16
	global_load_dwordx2 v[242:243], v[204:205], off offset:32
	global_load_dwordx2 v[244:245], v[204:205], off offset:48
	global_load_dwordx2 v[246:247], v[204:205], off offset:64
	global_load_dwordx2 v[248:249], v[204:205], off offset:80
	global_load_dwordx2 v[224:225], v[204:205], off offset:96
	global_load_dwordx2 v[226:227], v[204:205], off offset:112
	s_add_u32 s10, s36, s10
	v_lshl_add_u64 v[2:3], v[2:3], 0, s[16:17]
	s_addc_u32 s11, s37, 0
	v_lshlrev_b64 v[10:11], 1, v[0:1]
	v_lshl_add_u64 v[8:9], v[2:3], 0, v[192:193]
	v_lshl_add_u64 v[0:1], s[4:5], 0, v[10:11]
	v_lshlrev_b32_e32 v192, 1, v134
	v_lshl_add_u64 v[2:3], s[10:11], 0, v[10:11]
	v_lshl_add_u64 v[0:1], v[0:1], 0, v[192:193]
	v_lshl_add_u64 v[4:5], v[2:3], 0, v[192:193]
	global_load_dwordx4 v[0:3], v[0:1], off
	s_nop 0
	global_load_dwordx4 v[4:7], v[4:5], off
	s_nop 0
	global_load_dwordx4 v[92:95], v[8:9], off
	global_load_dwordx4 v[88:91], v[8:9], off offset:32
	global_load_dwordx4 v[84:87], v[8:9], off offset:64
	global_load_dwordx4 v[96:99], v[8:9], off offset:96
	v_readlane_b32 s10, v255, 22
	s_add_u32 s4, s50, s10
	s_addc_u32 s5, s51, 0
	s_add_u32 s10, s36, s10
	v_mul_u32_u24_e32 v12, 0x90, v209
	v_lshl_add_u64 v[8:9], s[4:5], 0, v[10:11]
	s_addc_u32 s11, s37, 0
	v_add_u32_e32 v196, v237, v12
	v_lshl_add_u64 v[8:9], v[8:9], 0, v[192:193]
	v_lshl_add_u64 v[12:13], s[10:11], 0, v[10:11]
	v_lshl_add_u64 v[12:13], v[12:13], 0, v[192:193]
	global_load_dwordx4 v[16:19], v[8:9], off
	global_load_dwordx4 v[38:41], v[12:13], off
	v_readlane_b32 s10, v255, 23
	s_add_u32 s4, s50, s10
	s_addc_u32 s5, s51, 0
	s_add_u32 s10, s36, s10
	v_lshl_add_u64 v[8:9], s[4:5], 0, v[10:11]
	s_addc_u32 s11, s37, 0
	v_lshl_add_u64 v[8:9], v[8:9], 0, v[192:193]
	v_lshl_add_u64 v[10:11], s[10:11], 0, v[10:11]
	v_lshl_add_u64 v[10:11], v[10:11], 0, v[192:193]
	global_load_dwordx4 v[66:69], v[8:9], off
	global_load_dwordx4 v[70:73], v[10:11], off
	s_barrier
	v_add_u32_e32 v197, v237, v208
	v_readlane_b32 s4, v255, 37
	v_readlane_b32 s5, v255, 38
	s_mov_b32 s5, s13
	s_mov_b32 s10, s4
	v_writelane_b32 v255, s10, 37
	s_waitcnt vmcnt(9)
	ds_write_b128 v207, v[0:3] offset:15360
	s_waitcnt vmcnt(8)
	ds_write_b128 v207, v[4:7] offset:24576
	s_waitcnt lgkmcnt(0)
	s_barrier
	ds_read_b128 v[0:3], v196 offset:15360
	ds_read_b128 v[42:45], v196 offset:15392
	s_waitcnt vmcnt(7) lgkmcnt(1)
	v_mfma_f32_32x32x16_bf16 v[0:15], v[0:3], v[92:95], 0
	ds_read_b128 v[20:23], v197 offset:15360
	ds_read_b128 v[46:49], v197 offset:15392
	v_writelane_b32 v255, s11, 38
	s_waitcnt lgkmcnt(1)
	v_mfma_f32_32x32x16_bf16 v[22:37], v[20:23], v[92:95], 0
	s_waitcnt vmcnt(6)
	v_mfma_f32_32x32x16_bf16 v[0:15], v[42:45], v[88:91], v[0:15]
	s_waitcnt lgkmcnt(0)
	v_mfma_f32_32x32x16_bf16 v[22:37], v[46:49], v[88:91], v[22:37]
	ds_read_b128 v[42:45], v196 offset:15424
	ds_read_b128 v[46:49], v196 offset:15456
	s_waitcnt vmcnt(5) lgkmcnt(1)
	v_mfma_f32_32x32x16_bf16 v[0:15], v[42:45], v[84:87], v[0:15]
	ds_read_b128 v[42:45], v197 offset:15424
	ds_read_b128 v[50:53], v197 offset:15456
	s_waitcnt lgkmcnt(1)
	v_mfma_f32_32x32x16_bf16 v[22:37], v[42:45], v[84:87], v[22:37]
	s_waitcnt vmcnt(4) lgkmcnt(0)
	v_mfma_f32_32x32x16_bf16 v[22:37], v[50:53], v[96:99], v[22:37]
	v_mfma_f32_32x32x16_bf16 v[0:15], v[46:49], v[96:99], v[0:15]
	s_nop 10
	v_max_f32_e32 v20, v23, v23
	v_max_f32_e32 v21, v22, v22
	v_max_f32_e32 v42, v25, v25
	v_max_f32_e32 v43, v24, v24
	v_max_f32_e32 v20, v21, v20
	v_max_f32_e32 v21, v43, v42
	v_max_f32_e32 v48, v27, v27
	v_max_f32_e32 v44, v1, v1
	v_max_f32_e32 v45, v0, v0
	v_max_f32_e32 v46, v3, v3
	v_max_f32_e32 v47, v2, v2
	v_max_f32_e32 v49, v26, v26
	v_max_f32_e32 v50, v29, v29
	v_max_f32_e32 v51, v28, v28
	v_max_f32_e32 v42, v45, v44
	v_max_f32_e32 v43, v47, v46
	v_max3_f32 v20, v20, s23, v21
	v_max_f32_e32 v52, v5, v5
	v_max_f32_e32 v53, v4, v4
	v_max_f32_e32 v54, v7, v7
	v_max_f32_e32 v55, v6, v6
	v_max_f32_e32 v44, v49, v48
	v_max_f32_e32 v45, v51, v50
	v_max3_f32 v20, v20, v42, v43
	v_max_f32_e32 v56, v31, v31
	v_max_f32_e32 v57, v30, v30
	v_max_f32_e32 v58, v33, v33
	v_max_f32_e32 v59, v32, v32
	v_max_f32_e32 v46, v53, v52
	v_max_f32_e32 v47, v55, v54
	v_max3_f32 v20, v20, v44, v45
	v_max_f32_e32 v60, v9, v9
	v_max_f32_e32 v61, v8, v8
	v_max_f32_e32 v62, v11, v11
	v_max_f32_e32 v63, v10, v10
	v_max_f32_e32 v48, v57, v56
	v_max_f32_e32 v49, v59, v58
	v_max3_f32 v20, v20, v46, v47
	v_max_f32_e32 v64, v35, v35
	v_max_f32_e32 v65, v34, v34
	v_max_f32_e32 v74, v37, v37
	v_max_f32_e32 v75, v36, v36
	v_max_f32_e32 v50, v61, v60
	v_max_f32_e32 v51, v63, v62
	v_max3_f32 v20, v20, v48, v49
	v_max_f32_e32 v76, v13, v13
	v_max_f32_e32 v77, v12, v12
	v_max_f32_e32 v78, v15, v15
	v_max_f32_e32 v79, v14, v14
	v_max_f32_e32 v52, v65, v64
	v_max_f32_e32 v53, v75, v74
	v_max3_f32 v20, v20, v50, v51
	v_max_f32_e32 v54, v77, v76
	v_max_f32_e32 v55, v79, v78
	v_max3_f32 v20, v20, v52, v53
	v_max3_f32 v44, v20, v54, v55
	ds_bpermute_b32 v45, v210, v44
	v_lshl_add_u64 v[42:43], v[136:137], 0, s[4:5]
	v_lshl_add_u64 v[20:21], v[138:139], 0, s[4:5]
	global_load_dwordx4 v[100:103], v[42:43], off
	global_load_dwordx4 v[104:107], v[20:21], off
	ds_read_b64_tr_b16 v[128:129], v211 offset:24576
	ds_read_b64_tr_b16 v[130:131], v211 offset:25728
	ds_read_b64_tr_b16 v[126:127], v211 offset:25792
	ds_read_b64_tr_b16 v[124:125], v211 offset:24640
	ds_read_b64_tr_b16 v[120:121], v211 offset:26880
	ds_read_b64_tr_b16 v[122:123], v211 offset:28032
	ds_read_b64_tr_b16 v[118:119], v211 offset:28096
	ds_read_b64_tr_b16 v[116:117], v211 offset:26944
	ds_read_b64_tr_b16 v[112:113], v211 offset:29184
	ds_read_b64_tr_b16 v[114:115], v211 offset:30336
	ds_read_b64_tr_b16 v[110:111], v211 offset:30400
	ds_read_b64_tr_b16 v[108:109], v211 offset:29248
	ds_read_b64_tr_b16 v[78:79], v211 offset:31488
	ds_read_b64_tr_b16 v[80:81], v211 offset:32640
	ds_read_b64_tr_b16 v[76:77], v211 offset:32704
	ds_read_b64_tr_b16 v[74:75], v211 offset:31552
	s_waitcnt lgkmcnt(14)
	v_max3_f32 v52, v44, v45, s23
	v_sub_f32_e32 v0, v0, v52
	v_exp_f32_e32 v140, v0
	v_sub_f32_e32 v0, v2, v52
	v_exp_f32_e32 v82, v0
	v_sub_f32_e32 v0, v3, v52
	v_exp_f32_e32 v134, v0
	v_sub_f32_e32 v0, v26, v52
	v_exp_f32_e32 v136, v0
	v_sub_f32_e32 v0, v27, v52
	v_exp_f32_e32 v146, v0
	v_sub_f32_e32 v0, v28, v52
	v_exp_f32_e32 v150, v0
	v_sub_f32_e32 v0, v29, v52
	v_exp_f32_e32 v152, v0
	v_sub_f32_e32 v0, v4, v52
	v_sub_f32_e32 v1, v1, v52
	v_exp_f32_e32 v148, v0
	v_sub_f32_e32 v0, v5, v52
	v_exp_f32_e32 v138, v1
	v_exp_f32_e32 v154, v0
	s_waitcnt vmcnt(5)
	ds_write_b128 v207, v[16:19] offset:33792
	s_waitcnt vmcnt(4)
	ds_write_b128 v207, v[38:41] offset:43008
	s_waitcnt lgkmcnt(0)
	s_barrier
	ds_read_b128 v[0:3], v196 offset:33792
	v_sub_f32_e32 v4, v6, v52
	v_exp_f32_e32 v158, v4
	v_sub_f32_e32 v4, v7, v52
	v_exp_f32_e32 v160, v4
	v_sub_f32_e32 v4, v30, v52
	v_sub_f32_e32 v20, v22, v52
	v_sub_f32_e32 v21, v23, v52
	v_sub_f32_e32 v22, v24, v52
	v_sub_f32_e32 v23, v25, v52
	v_exp_f32_e32 v162, v4
	ds_read_b128 v[4:7], v196 offset:33824
	v_exp_f32_e32 v192, v20
	v_exp_f32_e32 v198, v21
	v_exp_f32_e32 v144, v22
	v_exp_f32_e32 v142, v23
	v_sub_f32_e32 v38, v31, v52
	s_waitcnt lgkmcnt(1)
	v_mfma_f32_32x32x16_bf16 v[16:31], v[0:3], v[92:95], 0
	v_sub_f32_e32 v0, v32, v52
	v_exp_f32_e32 v164, v0
	v_sub_f32_e32 v0, v33, v52
	v_exp_f32_e32 v166, v0
	ds_read_b128 v[0:3], v196 offset:33856
	v_sub_f32_e32 v8, v8, v52
	v_exp_f32_e32 v170, v8
	s_waitcnt lgkmcnt(1)
	v_mfma_f32_32x32x16_bf16 v[16:31], v[4:7], v[88:91], v[16:31]
	v_sub_f32_e32 v4, v9, v52
	v_exp_f32_e32 v172, v4
	v_sub_f32_e32 v4, v10, v52
	v_exp_f32_e32 v174, v4
	ds_read_b128 v[4:7], v196 offset:33888
	v_sub_f32_e32 v8, v11, v52
	v_exp_f32_e32 v168, v38
	s_waitcnt lgkmcnt(1)
	v_mfma_f32_32x32x16_bf16 v[16:31], v[0:3], v[84:87], v[16:31]
	v_sub_f32_e32 v0, v34, v52
	v_exp_f32_e32 v176, v0
	v_sub_f32_e32 v0, v35, v52
	v_exp_f32_e32 v178, v0
	ds_read_b128 v[0:3], v197 offset:33792
	v_exp_f32_e32 v180, v8
	v_sub_f32_e32 v8, v36, v52
	s_waitcnt lgkmcnt(1)
	v_mfma_f32_32x32x16_bf16 v[16:31], v[4:7], v[96:99], v[16:31]
	v_sub_f32_e32 v4, v37, v52
	v_exp_f32_e32 v184, v4
	v_sub_f32_e32 v4, v12, v52
	v_exp_f32_e32 v186, v4
	ds_read_b128 v[4:7], v197 offset:33824
	v_exp_f32_e32 v182, v8
	v_sub_f32_e32 v8, v13, v52
	s_waitcnt lgkmcnt(1)
	v_mfma_f32_32x32x16_bf16 v[32:47], v[0:3], v[92:95], 0
	v_exp_f32_e32 v188, v8
	ds_read_b128 v[8:11], v197 offset:33856
	v_sub_f32_e32 v48, 0xf149f2ca, v52
	v_exp_f32_e32 v1, v48
	ds_read_b128 v[48:51], v197 offset:33888
	v_sub_f32_e32 v0, v14, v52
	v_exp_f32_e32 v190, v0
	s_waitcnt lgkmcnt(2)
	v_mfma_f32_32x32x16_bf16 v[32:47], v[4:7], v[88:91], v[32:47]
	v_sub_f32_e32 v0, v15, v52
	v_exp_f32_e32 v156, v0
	v_mul_f32_e32 v0, 0, v1
	v_mov_b32_e32 v1, v0
	v_mov_b32_e32 v2, v0
	v_mov_b32_e32 v3, v0
	v_mov_b32_e32 v4, v0
	s_waitcnt lgkmcnt(1)
	v_mfma_f32_32x32x16_bf16 v[32:47], v[8:11], v[84:87], v[32:47]
	v_mov_b32_e32 v5, v0
	v_mov_b32_e32 v6, v0
	v_mov_b32_e32 v7, v0
	v_mov_b32_e32 v8, v0
	v_mov_b32_e32 v9, v0
	v_mov_b32_e32 v10, v0
	v_mov_b32_e32 v11, v0
	s_waitcnt lgkmcnt(0)
	v_mfma_f32_32x32x16_bf16 v[32:47], v[48:51], v[96:99], v[32:47]
	v_max_f32_e32 v48, v18, v18
	v_mov_b32_e32 v12, v0
	v_cvt_pk_bf16_f32 v200, v192, v198
	v_cvt_pk_bf16_f32 v201, v144, v142
	v_cvt_pk_bf16_f32 v202, v136, v146
	v_cvt_pk_bf16_f32 v203, v150, v152
	s_nop 5
	v_max_f32_e32 v13, v33, v33
	v_max_f32_e32 v14, v32, v32
	v_max_f32_e32 v13, v14, v13
	v_max_f32_e32 v14, v35, v35
	v_max_f32_e32 v15, v34, v34
	v_max_f32_e32 v14, v15, v14
	v_max3_f32 v13, v13, s23, v14
	v_max_f32_e32 v14, v17, v17
	v_max_f32_e32 v15, v16, v16
	v_max_f32_e32 v14, v15, v14
	v_max_f32_e32 v15, v19, v19
	v_max_f32_e32 v15, v48, v15
	v_max3_f32 v13, v13, v14, v15
	v_max_f32_e32 v14, v37, v37
	v_max_f32_e32 v15, v36, v36
	v_max_f32_e32 v14, v15, v14
	v_max_f32_e32 v15, v39, v39
	v_max_f32_e32 v48, v38, v38
	v_max_f32_e32 v15, v48, v15
	v_max3_f32 v13, v13, v14, v15
	v_max_f32_e32 v14, v21, v21
	v_max_f32_e32 v15, v20, v20
	v_max_f32_e32 v14, v15, v14
	v_max_f32_e32 v15, v23, v23
	v_max_f32_e32 v48, v22, v22
	v_max_f32_e32 v15, v48, v15
	v_max3_f32 v13, v13, v14, v15
	v_max_f32_e32 v14, v41, v41
	v_max_f32_e32 v15, v40, v40
	v_max_f32_e32 v14, v15, v14
	v_max_f32_e32 v15, v43, v43
	v_max_f32_e32 v48, v42, v42
	v_max_f32_e32 v15, v48, v15
	v_max3_f32 v13, v13, v14, v15
	v_max_f32_e32 v14, v25, v25
	v_max_f32_e32 v15, v24, v24
	v_max_f32_e32 v14, v15, v14
	v_max_f32_e32 v15, v27, v27
	v_max_f32_e32 v48, v26, v26
	v_max_f32_e32 v15, v48, v15
	v_max3_f32 v13, v13, v14, v15
	v_max_f32_e32 v14, v45, v45
	v_max_f32_e32 v15, v44, v44
	v_max_f32_e32 v14, v15, v14
	v_max_f32_e32 v15, v47, v47
	v_max_f32_e32 v48, v46, v46
	v_max_f32_e32 v15, v48, v15
	v_max3_f32 v13, v13, v14, v15
	v_max_f32_e32 v14, v29, v29
	v_max_f32_e32 v15, v28, v28
	v_max_f32_e32 v14, v15, v14
	v_max_f32_e32 v15, v31, v31
	v_max_f32_e32 v48, v30, v30
	v_max_f32_e32 v15, v48, v15
	v_max3_f32 v48, v13, v14, v15
	ds_bpermute_b32 v49, v210, v48
	v_mov_b32_e32 v13, v0
	v_mov_b32_e32 v14, v0
	v_mov_b32_e32 v15, v0
	s_waitcnt lgkmcnt(0)
	v_max3_f32 v199, v52, v48, v49
	v_sub_f32_e32 v16, v16, v199
	v_exp_f32_e32 v83, v16
	v_sub_f32_e32 v16, v17, v199
	v_exp_f32_e32 v135, v16
	v_sub_f32_e32 v16, v18, v199
	v_exp_f32_e32 v137, v16
	v_sub_f32_e32 v16, v19, v199
	v_exp_f32_e32 v147, v16
	v_sub_f32_e32 v16, v36, v199
	v_exp_f32_e32 v151, v16
	v_sub_f32_e32 v16, v37, v199
	v_exp_f32_e32 v153, v16
	v_sub_f32_e32 v16, v38, v199
	v_exp_f32_e32 v149, v16
	v_sub_f32_e32 v16, v39, v199
	v_exp_f32_e32 v155, v16
	v_sub_f32_e32 v16, v20, v199
	v_exp_f32_e32 v159, v16
	v_sub_f32_e32 v16, v21, v199
	v_sub_f32_e32 v48, v52, v199
	v_mfma_f32_32x32x16_bf16 v[50:65], v[128:131], v[200:203], v[0:15]
	v_exp_f32_e32 v161, v16
	v_mov_b64_e32 v[16:17], v[14:15]
	v_sub_f32_e32 v18, v22, v199
	v_exp_f32_e32 v163, v18
	v_cvt_pk_bf16_f32 v18, v162, v168
	s_nop 1
	v_mov_b64_e32 v[14:15], v[12:13]
	v_mov_b64_e32 v[12:13], v[10:11]
	v_mov_b64_e32 v[10:11], v[8:9]
	v_mov_b64_e32 v[8:9], v[6:7]
	v_mov_b64_e32 v[6:7], v[4:5]
	v_mov_b64_e32 v[4:5], v[2:3]
	v_mov_b64_e32 v[2:3], v[0:1]
	v_cvt_pk_bf16_f32 v19, v164, v166
	v_cvt_pk_bf16_f32 v20, v176, v178
	v_mfma_f32_32x32x16_bf16 v[2:17], v[124:127], v[200:203], v[2:17]
	v_cvt_pk_bf16_f32 v21, v182, v184
	v_sub_f32_e32 v1, v23, v199
	v_exp_f32_e32 v169, v1
	v_sub_f32_e32 v1, v40, v199
	v_cvt_pk_bf16_f32 v22, v186, v188
	v_cvt_pk_bf16_f32 v23, v190, v156
	v_sub_f32_e32 v32, v32, v199
	v_mfma_f32_32x32x16_bf16 v[50:65], v[120:123], v[18:21], v[50:65]
	v_exp_f32_e32 v165, v1
	v_sub_f32_e32 v1, v41, v199
	v_exp_f32_e32 v145, v32
	v_sub_f32_e32 v32, v33, v199
	v_exp_f32_e32 v167, v1
	v_sub_f32_e32 v1, v42, v199
	v_exp_f32_e32 v143, v32
	v_mfma_f32_32x32x16_bf16 v[2:17], v[116:119], v[18:21], v[2:17]
	v_cvt_pk_bf16_f32 v18, v140, v138
	v_cvt_pk_bf16_f32 v19, v82, v134
	v_cvt_pk_bf16_f32 v20, v148, v154
	v_cvt_pk_bf16_f32 v21, v158, v160
	v_sub_f32_e32 v32, v34, v199
	v_exp_f32_e32 v171, v1
	v_sub_f32_e32 v1, v43, v199
	v_mfma_f32_32x32x16_bf16 v[50:65], v[112:115], v[18:21], v[50:65]
	v_exp_f32_e32 v141, v32
	v_sub_f32_e32 v32, v35, v199
	v_exp_f32_e32 v173, v1
	v_sub_f32_e32 v1, v24, v199
	v_exp_f32_e32 v139, v32
	v_exp_f32_e32 v175, v1
	v_sub_f32_e32 v1, v25, v199
	v_mfma_f32_32x32x16_bf16 v[2:17], v[108:111], v[18:21], v[2:17]
	v_cvt_pk_bf16_f32 v20, v170, v172
	v_cvt_pk_bf16_f32 v21, v174, v180
	v_exp_f32_e32 v18, v48
	v_exp_f32_e32 v181, v1
	v_sub_f32_e32 v1, v44, v199
	v_exp_f32_e32 v183, v1
	v_sub_f32_e32 v1, v45, v199
	v_mfma_f32_32x32x16_bf16 v[50:65], v[78:81], v[20:23], v[50:65]
	ds_read_b64_tr_b16 v[78:79], v211 offset:43008
	ds_read_b64_tr_b16 v[80:81], v211 offset:44160
	ds_read_b64_tr_b16 v[110:111], v211 offset:44224
	ds_read_b64_tr_b16 v[108:109], v211 offset:43072
	ds_read_b64_tr_b16 v[112:113], v211 offset:45312
	ds_read_b64_tr_b16 v[114:115], v211 offset:46464
	v_exp_f32_e32 v185, v1
	v_sub_f32_e32 v1, v46, v199
	v_exp_f32_e32 v187, v1
	v_sub_f32_e32 v1, v47, v199
	v_cvt_pk_bf16_f32 v116, v145, v143
	v_cvt_pk_bf16_f32 v117, v141, v139
	v_mfma_f32_32x32x16_bf16 v[2:17], v[74:77], v[20:23], v[2:17]
	v_cvt_pk_bf16_f32 v118, v151, v153
	v_cvt_pk_bf16_f32 v119, v149, v155
	v_mul_f32_e64 v48, v64, v18
	v_mul_f32_e64 v49, v65, v18
	v_mul_f32_e64 v46, v62, v18
	v_mul_f32_e64 v47, v63, v18
	v_pk_mul_f32 v[44:45], v[60:61], v[18:19] op_sel_hi:[1,0]
	v_pk_mul_f32 v[42:43], v[58:59], v[18:19] op_sel_hi:[1,0]
	v_pk_mul_f32 v[40:41], v[56:57], v[18:19] op_sel_hi:[1,0]
	v_pk_mul_f32 v[38:39], v[54:55], v[18:19] op_sel_hi:[1,0]
	v_pk_mul_f32 v[36:37], v[52:53], v[18:19] op_sel_hi:[1,0]
	v_pk_mul_f32 v[34:35], v[50:51], v[18:19] op_sel_hi:[1,0]
	v_pk_mul_f32 v[16:17], v[16:17], v[18:19] op_sel_hi:[1,0]
	v_pk_mul_f32 v[14:15], v[14:15], v[18:19] op_sel_hi:[1,0]
	v_pk_mul_f32 v[12:13], v[12:13], v[18:19] op_sel_hi:[1,0]
	v_pk_mul_f32 v[10:11], v[10:11], v[18:19] op_sel_hi:[1,0]
	v_pk_mul_f32 v[8:9], v[8:9], v[18:19] op_sel_hi:[1,0]
	v_pk_mul_f32 v[6:7], v[6:7], v[18:19] op_sel_hi:[1,0]
	v_pk_mul_f32 v[4:5], v[4:5], v[18:19] op_sel_hi:[1,0]
	v_pk_mul_f32 v[2:3], v[2:3], v[18:19] op_sel_hi:[1,0]
	s_waitcnt lgkmcnt(4)
	v_mfma_f32_32x32x16_bf16 v[34:49], v[78:81], v[116:119], v[34:49]
	v_exp_f32_e32 v189, v1
	ds_read_b64_tr_b16 v[22:23], v211 offset:46528
	ds_read_b64_tr_b16 v[20:21], v211 offset:45376
	v_cvt_pk_bf16_f32 v50, v165, v167
	v_cvt_pk_bf16_f32 v51, v171, v173
	v_cvt_pk_bf16_f32 v52, v183, v185
	v_cvt_pk_bf16_f32 v53, v187, v189
	v_sub_f32_e32 v1, v26, v199
	s_waitcnt lgkmcnt(4)
	v_mfma_f32_32x32x16_bf16 v[2:17], v[108:111], v[116:119], v[2:17]
	v_exp_f32_e32 v177, v1
	v_sub_f32_e32 v1, v27, v199
	ds_read_b64_tr_b16 v[24:25], v211 offset:47616
	ds_read_b64_tr_b16 v[26:27], v211 offset:48768
	v_exp_f32_e32 v179, v1
	v_sub_f32_e32 v1, v28, v199
	v_exp_f32_e32 v191, v1
	v_sub_f32_e32 v1, v29, v199
	s_waitcnt lgkmcnt(4)
	v_mfma_f32_32x32x16_bf16 v[34:49], v[112:115], v[50:53], v[34:49]
	v_exp_f32_e32 v157, v1
	v_sub_f32_e32 v1, v30, v199
	v_sub_f32_e32 v19, v31, v199
	v_exp_f32_e32 v1, v1
	v_exp_f32_e32 v19, v19
	v_cvt_pk_bf16_f32 v28, v175, v181
	v_cvt_pk_bf16_f32 v29, v177, v179
	s_waitcnt lgkmcnt(2)
	v_mfma_f32_32x32x16_bf16 v[2:17], v[20:23], v[50:53], v[2:17]
	ds_read_b64_tr_b16 v[22:23], v211 offset:48832
	ds_read_b64_tr_b16 v[20:21], v211 offset:47680
	v_cvt_pk_bf16_f32 v50, v83, v135
	v_cvt_pk_bf16_f32 v51, v137, v147
	v_cvt_pk_bf16_f32 v52, v159, v161
	v_cvt_pk_bf16_f32 v53, v163, v169
	v_cvt_pk_bf16_f32 v30, v191, v157
	v_cvt_pk_bf16_f32 v31, v1, v19
	s_waitcnt lgkmcnt(2)
	v_mfma_f32_32x32x16_bf16 v[34:49], v[24:27], v[50:53], v[34:49]
	ds_read_b64_tr_b16 v[24:25], v211 offset:49920
	ds_read_b64_tr_b16 v[26:27], v211 offset:51072
	s_waitcnt lgkmcnt(2)
	v_mfma_f32_32x32x16_bf16 v[2:17], v[20:23], v[50:53], v[2:17]
	ds_read_b64_tr_b16 v[22:23], v211 offset:51136
	ds_read_b64_tr_b16 v[20:21], v211 offset:49984
	s_waitcnt vmcnt(3)
	ds_write_b128 v207, v[66:69] offset:15360
	s_waitcnt vmcnt(2)
	ds_write_b128 v207, v[70:73] offset:24576
	s_waitcnt lgkmcnt(0)
	s_barrier
	v_mfma_f32_32x32x16_bf16 v[34:49], v[24:27], v[28:31], v[34:49]
	v_mfma_f32_32x32x16_bf16 v[2:17], v[20:23], v[28:31], v[2:17]
	ds_read_b128 v[20:23], v196 offset:15360
	ds_read_b128 v[24:27], v196 offset:15392
	s_waitcnt lgkmcnt(1)
	v_mfma_f32_32x32x16_bf16 v[52:67], v[20:23], v[92:95], 0
	s_waitcnt lgkmcnt(0)
	v_mfma_f32_32x32x16_bf16 v[52:67], v[24:27], v[88:91], v[52:67]
	ds_read_b128 v[20:23], v196 offset:15424
	ds_read_b128 v[24:27], v196 offset:15456
	s_waitcnt lgkmcnt(1)
	v_mfma_f32_32x32x16_bf16 v[52:67], v[20:23], v[84:87], v[52:67]
	v_add_f32_e32 v20, 0, v192
	v_add_f32_e32 v192, v198, v20
	v_add_f32_e64 v20, v144, v192
	v_add_f32_e64 v21, v145, v193
	v_add_f32_e64 v20, v142, v20
	v_add_f32_e64 v21, v143, v21
	v_pk_add_f32 v[20:21], v[140:141], v[20:21]
	s_waitcnt lgkmcnt(0)
	v_mfma_f32_32x32x16_bf16 v[52:67], v[24:27], v[96:99], v[52:67]
	v_add_f32_e64 v28, v138, v20
	v_add_f32_e64 v29, v139, v21
	ds_read_b128 v[20:23], v197 offset:15360
	v_add_f32_e64 v24, v82, v28
	v_add_f32_e64 v25, v83, v29
	v_pk_add_f32 v[24:25], v[134:135], v[24:25]
	s_nop 0
	v_pk_add_f32 v[24:25], v[136:137], v[24:25]
	s_nop 0
	v_pk_add_f32 v[24:25], v[146:147], v[24:25]
	s_nop 0
	v_pk_add_f32 v[24:25], v[150:151], v[24:25]
	s_nop 0
	v_pk_add_f32 v[28:29], v[152:153], v[24:25]
	ds_read_b128 v[24:27], v197 offset:15392
	s_waitcnt lgkmcnt(1)
	v_mfma_f32_32x32x16_bf16 v[68:83], v[20:23], v[92:95], 0
	v_add_f32_e64 v20, v148, v28
	v_add_f32_e64 v21, v149, v29
	v_add_f32_e64 v20, v154, v20
	v_add_f32_e64 v21, v155, v21
	v_add_f32_e64 v20, v158, v20
	v_add_f32_e64 v21, v159, v21
	v_pk_add_f32 v[20:21], v[160:161], v[20:21]
	s_waitcnt lgkmcnt(0)
	v_mfma_f32_32x32x16_bf16 v[68:83], v[24:27], v[88:91], v[68:83]
	v_add_f32_e64 v20, v162, v20
	v_add_f32_e64 v21, v163, v21
	v_add_f32_e64 v28, v168, v20
	v_add_f32_e64 v29, v169, v21
	ds_read_b128 v[20:23], v197 offset:15424
	v_pk_add_f32 v[24:25], v[164:165], v[28:29]
	s_nop 0
	v_pk_add_f32 v[24:25], v[166:167], v[24:25]
	s_nop 0
	v_pk_add_f32 v[24:25], v[170:171], v[24:25]
	s_nop 0
	v_pk_add_f32 v[24:25], v[172:173], v[24:25]
	s_nop 0
	v_pk_add_f32 v[24:25], v[174:175], v[24:25]
	s_nop 0
	v_pk_add_f32 v[28:29], v[180:181], v[24:25]
	ds_read_b128 v[24:27], v197 offset:15456
	s_waitcnt lgkmcnt(1)
	v_mfma_f32_32x32x16_bf16 v[68:83], v[20:23], v[84:87], v[68:83]
	v_add_f32_e64 v20, v176, v28
	v_add_f32_e64 v21, v177, v29
	v_add_f32_e64 v20, v178, v20
	v_add_f32_e64 v21, v179, v21
	v_add_f32_e64 v20, v182, v20
	v_add_f32_e64 v21, v183, v21
	v_pk_add_f32 v[20:21], v[184:185], v[20:21]
	s_waitcnt lgkmcnt(0)
	v_mfma_f32_32x32x16_bf16 v[68:83], v[24:27], v[96:99], v[68:83]
	v_max_f32_e32 v25, v54, v54
	v_add_f32_e64 v20, v186, v20
	v_add_f32_e64 v21, v187, v21
	v_add_f32_e64 v20, v188, v20
	v_add_f32_e64 v21, v189, v21
	v_pk_add_f32 v[20:21], v[190:191], v[20:21]
	s_nop 5
	v_max_f32_e32 v22, v69, v69
	v_max_f32_e32 v23, v68, v68
	v_max_f32_e32 v22, v23, v22
	v_max_f32_e32 v23, v71, v71
	v_max_f32_e32 v24, v70, v70
	v_max_f32_e32 v23, v24, v23
	v_max3_f32 v22, v22, s23, v23
	v_max_f32_e32 v23, v53, v53
	v_max_f32_e32 v24, v52, v52
	v_max_f32_e32 v23, v24, v23
	v_max_f32_e32 v24, v55, v55
	v_max_f32_e32 v24, v25, v24
	v_max3_f32 v22, v22, v23, v24
	v_max_f32_e32 v23, v73, v73
	v_max_f32_e32 v24, v72, v72
	v_max_f32_e32 v23, v24, v23
	v_max_f32_e32 v24, v75, v75
	v_max_f32_e32 v25, v74, v74
	v_max_f32_e32 v24, v25, v24
	v_max3_f32 v22, v22, v23, v24
	v_max_f32_e32 v23, v57, v57
	v_max_f32_e32 v24, v56, v56
	v_max_f32_e32 v23, v24, v23
	v_max_f32_e32 v24, v59, v59
	v_max_f32_e32 v25, v58, v58
	v_max_f32_e32 v24, v25, v24
	v_max3_f32 v22, v22, v23, v24
	v_max_f32_e32 v23, v77, v77
	v_max_f32_e32 v24, v76, v76
	v_max_f32_e32 v23, v24, v23
	v_max_f32_e32 v24, v79, v79
	v_max_f32_e32 v25, v78, v78
	v_max_f32_e32 v24, v25, v24
	v_max3_f32 v22, v22, v23, v24
	v_max_f32_e32 v23, v61, v61
	v_max_f32_e32 v24, v60, v60
	v_max_f32_e32 v23, v24, v23
	v_max_f32_e32 v24, v63, v63
	v_max_f32_e32 v25, v62, v62
	v_max_f32_e32 v24, v25, v24
	v_max3_f32 v22, v22, v23, v24
	v_max_f32_e32 v23, v81, v81
	v_max_f32_e32 v24, v80, v80
	v_max_f32_e32 v23, v24, v23
	v_max_f32_e32 v24, v83, v83
	v_max_f32_e32 v25, v82, v82
	v_max_f32_e32 v24, v25, v24
	v_max3_f32 v22, v22, v23, v24
	v_max_f32_e32 v23, v65, v65
	v_max_f32_e32 v24, v64, v64
	v_max_f32_e32 v23, v24, v23
	v_max_f32_e32 v24, v67, v67
	v_max_f32_e32 v25, v66, v66
	v_max_f32_e32 v24, v25, v24
	v_max3_f32 v22, v22, v23, v24
	ds_bpermute_b32 v23, v210, v22
	v_pk_add_f32 v[20:21], v[156:157], v[20:21]
	s_waitcnt lgkmcnt(0)
	v_max3_f32 v125, v199, v22, v23
	v_pk_add_f32 v[0:1], v[0:1], v[20:21]
	v_sub_f32_e32 v22, v58, v125
	v_add_f32_e32 v1, v1, v19
	v_sub_f32_e32 v19, v68, v125
	v_fmac_f32_e32 v1, v0, v18
	v_sub_f32_e32 v18, v55, v125
	v_exp_f32_e32 v127, v19
	v_sub_f32_e32 v19, v69, v125
	v_exp_f32_e32 v124, v18
	v_sub_f32_e32 v18, v72, v125
	v_exp_f32_e32 v129, v19
	v_exp_f32_e32 v126, v18
	v_sub_f32_e32 v18, v73, v125
	v_exp_f32_e32 v128, v18
	v_sub_f32_e32 v18, v74, v125
	v_exp_f32_e32 v144, v18
	v_sub_f32_e32 v18, v75, v125
	v_add_f32_e32 v0, 0, v127
	v_exp_f32_e32 v146, v18
	v_sub_f32_e32 v18, v56, v125
	v_add_f32_e32 v192, v129, v0
	v_sub_f32_e32 v0, v70, v125
	v_exp_f32_e32 v130, v18
	v_sub_f32_e32 v18, v57, v125
	v_exp_f32_e32 v136, v0
	v_sub_f32_e32 v0, v71, v125
	v_exp_f32_e32 v134, v18
	ds_read_b64_tr_b16 v[164:165], v211 offset:24576
	ds_read_b64_tr_b16 v[166:167], v211 offset:25728
	ds_read_b64_tr_b16 v[170:171], v211 offset:25792
	ds_read_b64_tr_b16 v[168:169], v211 offset:24640
	ds_read_b64_tr_b16 v[120:121], v211 offset:26880
	ds_read_b64_tr_b16 v[122:123], v211 offset:28032
	ds_read_b64_tr_b16 v[114:115], v211 offset:28096
	ds_read_b64_tr_b16 v[112:113], v211 offset:26944
	ds_read_b64_tr_b16 v[116:117], v211 offset:29184
	ds_read_b64_tr_b16 v[118:119], v211 offset:30336
	ds_read_b64_tr_b16 v[110:111], v211 offset:30400
	ds_read_b64_tr_b16 v[108:109], v211 offset:29248
	ds_read_b64_tr_b16 v[72:73], v211 offset:31488
	ds_read_b64_tr_b16 v[74:75], v211 offset:32640
	ds_read_b64_tr_b16 v[70:71], v211 offset:32704
	ds_read_b64_tr_b16 v[68:69], v211 offset:31552
	s_waitcnt vmcnt(1)
	ds_write_b128 v207, v[100:103] offset:33792
	s_waitcnt vmcnt(0)
	ds_write_b128 v207, v[104:107] offset:43008
	s_waitcnt lgkmcnt(0)
	s_barrier
	ds_read_b128 v[18:21], v196 offset:33792
	v_exp_f32_e32 v100, v22
	v_sub_f32_e32 v22, v59, v125
	v_exp_f32_e32 v138, v0
	v_sub_f32_e32 v0, v52, v125
	v_exp_f32_e32 v102, v22
	v_sub_f32_e32 v22, v76, v125
	v_exp_f32_e32 v140, v0
	v_sub_f32_e32 v0, v53, v125
	v_exp_f32_e32 v76, v22
	v_sub_f32_e32 v22, v77, v125
	ds_read_b128 v[50:53], v196 offset:33824
	v_exp_f32_e32 v104, v22
	s_waitcnt lgkmcnt(1)
	v_mfma_f32_32x32x16_bf16 v[18:33], v[18:21], v[92:95], 0
	v_exp_f32_e32 v142, v0
	v_sub_f32_e32 v0, v54, v125
	v_sub_f32_e32 v54, v78, v125
	v_exp_f32_e32 v150, v54
	v_sub_f32_e32 v54, v79, v125
	v_exp_f32_e32 v154, v54
	v_sub_f32_e32 v54, v60, v125
	v_exp_f32_e32 v158, v54
	ds_read_b128 v[54:57], v196 offset:33856
	s_waitcnt lgkmcnt(1)
	v_mfma_f32_32x32x16_bf16 v[18:33], v[50:53], v[88:91], v[18:33]
	v_sub_f32_e32 v50, v61, v125
	v_exp_f32_e32 v162, v50
	v_sub_f32_e32 v50, v62, v125
	v_exp_f32_e32 v78, v50
	v_sub_f32_e32 v50, v63, v125
	v_exp_f32_e32 v106, v50
	ds_read_b128 v[50:53], v196 offset:33888
	s_waitcnt lgkmcnt(1)
	v_mfma_f32_32x32x16_bf16 v[18:33], v[54:57], v[84:87], v[18:33]
	v_sub_f32_e32 v54, v80, v125
	v_exp_f32_e32 v80, v54
	v_sub_f32_e32 v54, v81, v125
	v_exp_f32_e32 v148, v54
	v_sub_f32_e32 v54, v82, v125
	v_exp_f32_e32 v82, v54
	ds_read_b128 v[54:57], v197 offset:33792
	ds_read_b128 v[172:175], v197 offset:33824
	s_waitcnt lgkmcnt(2)
	v_mfma_f32_32x32x16_bf16 v[18:33], v[50:53], v[96:99], v[18:33]
	v_sub_f32_e32 v50, v83, v125
	v_exp_f32_e32 v152, v50
	v_sub_f32_e32 v50, v64, v125
	v_exp_f32_e32 v156, v50
	v_sub_f32_e32 v50, v65, v125
	v_exp_f32_e32 v160, v50
	ds_read_b128 v[176:179], v197 offset:33856
	s_waitcnt lgkmcnt(2)
	v_mfma_f32_32x32x16_bf16 v[50:65], v[54:57], v[92:95], 0
	v_sub_f32_e32 v131, v199, v125
	v_exp_f32_e32 v180, v131
	v_sub_f32_e32 v67, v67, v125
	v_exp_f32_e32 v94, v67
	v_max_f32_e32 v79, v20, v20
	v_mul_f32_e32 v92, v1, v180
	v_pk_mul_f32 v[48:49], v[48:49], v[180:181] op_sel_hi:[1,0]
	s_waitcnt lgkmcnt(1)
	v_mfma_f32_32x32x16_bf16 v[50:65], v[172:175], v[88:91], v[50:65]
	ds_read_b128 v[88:91], v197 offset:33888
	v_mul_f32_e64 v46, v46, v180
	v_mul_f32_e64 v47, v47, v180
	v_mul_f32_e64 v44, v44, v180
	v_mul_f32_e64 v45, v45, v180
	v_pk_mul_f32 v[42:43], v[42:43], v[180:181] op_sel_hi:[1,0]
	v_pk_mul_f32 v[40:41], v[40:41], v[180:181] op_sel_hi:[1,0]
	v_pk_mul_f32 v[38:39], v[38:39], v[180:181] op_sel_hi:[1,0]
	v_pk_mul_f32 v[36:37], v[36:37], v[180:181] op_sel_hi:[1,0]
	s_waitcnt lgkmcnt(1)
	v_mfma_f32_32x32x16_bf16 v[50:65], v[176:179], v[84:87], v[50:65]
	v_mul_f32_e64 v34, v34, v180
	v_mul_f32_e64 v35, v35, v180
	v_mul_f32_e64 v16, v16, v180
	v_mul_f32_e64 v17, v17, v180
	v_mul_f32_e64 v14, v14, v180
	v_mul_f32_e64 v15, v15, v180
	v_pk_mul_f32 v[12:13], v[12:13], v[180:181] op_sel_hi:[1,0]
	v_pk_mul_f32 v[10:11], v[10:11], v[180:181] op_sel_hi:[1,0]
	v_pk_mul_f32 v[8:9], v[8:9], v[180:181] op_sel_hi:[1,0]
	v_pk_mul_f32 v[6:7], v[6:7], v[180:181] op_sel_hi:[1,0]
	s_waitcnt lgkmcnt(0)
	v_mfma_f32_32x32x16_bf16 v[50:65], v[88:91], v[96:99], v[50:65]
	v_mul_f32_e64 v4, v4, v180
	v_mul_f32_e64 v5, v5, v180
	v_mul_f32_e64 v2, v2, v180
	v_mul_f32_e64 v3, v3, v180
	v_cvt_pk_bf16_f32 v84, v127, v129
	v_cvt_pk_bf16_f32 v85, v136, v138
	v_cvt_pk_bf16_f32 v86, v126, v128
	v_cvt_pk_bf16_f32 v87, v144, v146
	v_sub_f32_e32 v66, v66, v125
	s_nop 2
	v_max_f32_e32 v1, v51, v51
	v_max_f32_e32 v67, v50, v50
	v_max_f32_e32 v1, v67, v1
	v_max_f32_e32 v67, v53, v53
	v_max_f32_e32 v77, v52, v52
	v_max_f32_e32 v67, v77, v67
	v_max3_f32 v1, v1, s23, v67
	v_max_f32_e32 v67, v19, v19
	v_max_f32_e32 v77, v18, v18
	v_max_f32_e32 v67, v77, v67
	v_max_f32_e32 v77, v21, v21
	v_max_f32_e32 v77, v79, v77
	v_max3_f32 v1, v1, v67, v77
	v_max_f32_e32 v67, v55, v55
	v_max_f32_e32 v77, v54, v54
	v_max_f32_e32 v67, v77, v67
	v_max_f32_e32 v77, v57, v57
	v_max_f32_e32 v79, v56, v56
	v_max_f32_e32 v77, v79, v77
	v_max3_f32 v1, v1, v67, v77
	v_max_f32_e32 v67, v23, v23
	v_max_f32_e32 v77, v22, v22
	v_max_f32_e32 v67, v77, v67
	v_max_f32_e32 v77, v25, v25
	v_max_f32_e32 v79, v24, v24
	v_max_f32_e32 v77, v79, v77
	v_max3_f32 v1, v1, v67, v77
	v_max_f32_e32 v67, v59, v59
	v_max_f32_e32 v77, v58, v58
	v_max_f32_e32 v67, v77, v67
	v_max_f32_e32 v77, v61, v61
	v_max_f32_e32 v79, v60, v60
	v_max_f32_e32 v77, v79, v77
	v_max3_f32 v1, v1, v67, v77
	v_max_f32_e32 v67, v27, v27
	v_max_f32_e32 v77, v26, v26
	v_max_f32_e32 v67, v77, v67
	v_max_f32_e32 v77, v29, v29
	v_max_f32_e32 v79, v28, v28
	v_max_f32_e32 v77, v79, v77
	v_max3_f32 v1, v1, v67, v77
	v_max_f32_e32 v67, v63, v63
	v_max_f32_e32 v77, v62, v62
	v_max_f32_e32 v67, v77, v67
	v_max_f32_e32 v77, v65, v65
	v_max_f32_e32 v79, v64, v64
	v_max_f32_e32 v77, v79, v77
	v_max3_f32 v1, v1, v67, v77
	v_max_f32_e32 v67, v31, v31
	v_max_f32_e32 v77, v30, v30
	v_max_f32_e32 v67, v77, v67
	v_max_f32_e32 v77, v33, v33
	v_max_f32_e32 v79, v32, v32
	v_max_f32_e32 v77, v79, v77
	v_max3_f32 v1, v1, v67, v77
	ds_bpermute_b32 v67, v210, v1
	v_mfma_f32_32x32x16_bf16 v[34:49], v[164:167], v[84:87], v[34:49]
	v_exp_f32_e32 v0, v0
	v_exp_f32_e32 v66, v66
	s_waitcnt lgkmcnt(0)
	v_max3_f32 v96, v125, v1, v67
	v_sub_f32_e32 v1, v50, v96
	v_exp_f32_e32 v137, v1
	v_sub_f32_e32 v1, v51, v96
	v_mfma_f32_32x32x16_bf16 v[2:17], v[168:171], v[84:87], v[2:17]
	v_exp_f32_e32 v139, v1
	v_sub_f32_e32 v1, v52, v96
	v_exp_f32_e32 v141, v1
	v_sub_f32_e32 v1, v53, v96
	v_exp_f32_e32 v143, v1
	v_sub_f32_e32 v1, v18, v96
	v_sub_f32_e32 v18, v19, v96
	v_sub_f32_e32 v67, v125, v96
	v_exp_f32_e32 v125, v18
	v_sub_f32_e32 v18, v20, v96
	v_exp_f32_e32 v127, v18
	v_sub_f32_e32 v18, v21, v96
	v_exp_f32_e32 v129, v18
	v_sub_f32_e32 v18, v54, v96
	v_exp_f32_e32 v1, v1
	v_exp_f32_e32 v145, v18
	v_pk_add_f32 v[18:19], v[136:137], v[192:193]
	v_cvt_pk_bf16_f32 v50, v76, v104
	v_cvt_pk_bf16_f32 v51, v150, v154
	v_cvt_pk_bf16_f32 v52, v80, v148
	v_cvt_pk_bf16_f32 v53, v82, v152
	v_pk_add_f32 v[18:19], v[138:139], v[18:19]
	v_cvt_pk_bf16_f32 v21, v0, v124
	v_mfma_f32_32x32x16_bf16 v[34:49], v[120:123], v[50:53], v[34:49]
	v_add_f32_e64 v18, v140, v18
	v_add_f32_e64 v19, v141, v19
	v_cvt_pk_bf16_f32 v20, v140, v142
	v_add_f32_e64 v18, v142, v18
	v_add_f32_e64 v19, v143, v19
	v_lshlrev_b32_e32 v192, 1, v206
	v_pk_add_f32 v[18:19], v[0:1], v[18:19]
	v_sub_f32_e32 v0, v55, v96
	v_exp_f32_e32 v147, v0
	v_mfma_f32_32x32x16_bf16 v[2:17], v[112:115], v[50:53], v[2:17]
	v_sub_f32_e32 v0, v56, v96
	v_exp_f32_e32 v131, v0
	v_sub_f32_e32 v0, v57, v96
	v_exp_f32_e32 v135, v0
	v_sub_f32_e32 v0, v22, v96
	v_exp_f32_e32 v101, v0
	v_sub_f32_e32 v0, v23, v96
	v_cvt_pk_bf16_f32 v22, v130, v134
	v_cvt_pk_bf16_f32 v23, v100, v102
	v_exp_f32_e32 v103, v0
	v_sub_f32_e32 v0, v24, v96
	v_mfma_f32_32x32x16_bf16 v[34:49], v[116:119], v[20:23], v[34:49]
	v_exp_f32_e32 v77, v0
	v_sub_f32_e32 v0, v25, v96
	v_exp_f32_e32 v105, v0
	v_sub_f32_e32 v0, v58, v96
	v_exp_f32_e32 v151, v0
	v_sub_f32_e32 v0, v59, v96
	v_exp_f32_e32 v155, v0
	v_mfma_f32_32x32x16_bf16 v[2:17], v[108:111], v[20:23], v[2:17]
	v_sub_f32_e32 v0, v60, v96
	v_exp_f32_e32 v159, v0
	v_sub_f32_e32 v0, v61, v96
	v_exp_f32_e32 v163, v0
	v_sub_f32_e32 v0, v26, v96
	v_cvt_pk_bf16_f32 v24, v158, v162
	v_exp_f32_e32 v79, v0
	v_sub_f32_e32 v0, v27, v96
	v_cvt_pk_bf16_f32 v25, v78, v106
	v_cvt_pk_bf16_f32 v26, v156, v160
	v_cvt_pk_bf16_f32 v27, v66, v94
	v_exp_f32_e32 v107, v0
	v_sub_f32_e32 v0, v28, v96
	v_mfma_f32_32x32x16_bf16 v[34:49], v[72:75], v[24:27], v[34:49]
	v_exp_f32_e32 v81, v0
	v_sub_f32_e32 v0, v29, v96
	v_pk_add_f32 v[18:19], v[124:125], v[18:19]
	v_exp_f32_e32 v149, v0
	v_sub_f32_e32 v0, v62, v96
	v_pk_add_f32 v[18:19], v[126:127], v[18:19]
	v_exp_f32_e32 v83, v0
	v_mfma_f32_32x32x16_bf16 v[2:17], v[68:71], v[24:27], v[2:17]
	v_sub_f32_e32 v0, v63, v96
	v_sub_f32_e32 v20, v64, v96
	v_add_f32_e64 v18, v128, v18
	v_add_f32_e64 v19, v129, v19
	v_exp_f32_e32 v153, v0
	v_exp_f32_e32 v0, v67
	v_exp_f32_e32 v157, v20
	ds_read_b64_tr_b16 v[20:21], v211 offset:43008
	ds_read_b64_tr_b16 v[22:23], v211 offset:44160
	ds_read_b64_tr_b16 v[26:27], v211 offset:44224
	ds_read_b64_tr_b16 v[24:25], v211 offset:43072
	v_lshlrev_b64 v[28:29], 11, v[132:133]
	v_pk_add_f32 v[18:19], v[144:145], v[18:19]
	v_lshl_add_u64 v[28:29], s[0:1], 0, v[28:29]
	v_pk_add_f32 v[18:19], v[146:147], v[18:19]
	v_lshl_add_u64 v[28:29], v[28:29], 0, s[16:17]
	v_pk_add_f32 v[18:19], v[130:131], v[18:19]
	v_lshl_add_u64 v[28:29], v[28:29], 0, v[192:193]
	v_pk_add_f32 v[18:19], v[134:135], v[18:19]
	v_pk_mul_f32 v[48:49], v[48:49], v[0:1] op_sel_hi:[1,0]
	v_pk_mul_f32 v[46:47], v[46:47], v[0:1] op_sel_hi:[1,0]
	v_pk_mul_f32 v[44:45], v[44:45], v[0:1] op_sel_hi:[1,0]
	v_pk_mul_f32 v[42:43], v[42:43], v[0:1] op_sel_hi:[1,0]
	v_pk_mul_f32 v[40:41], v[40:41], v[0:1] op_sel_hi:[1,0]
	v_pk_mul_f32 v[38:39], v[38:39], v[0:1] op_sel_hi:[1,0]
	v_pk_mul_f32 v[36:37], v[36:37], v[0:1] op_sel_hi:[1,0]
	v_pk_mul_f32 v[34:35], v[34:35], v[0:1] op_sel_hi:[1,0]
	v_pk_mul_f32 v[16:17], v[16:17], v[0:1] op_sel_hi:[1,0]
	v_cvt_pk_bf16_f32 v50, v137, v139
	v_cvt_pk_bf16_f32 v51, v141, v143
	v_cvt_pk_bf16_f32 v52, v145, v147
	ds_read_b64_tr_b16 v[54:55], v211 offset:45312
	ds_read_b64_tr_b16 v[56:57], v211 offset:46464
	ds_read_b64_tr_b16 v[60:61], v211 offset:46528
	ds_read_b64_tr_b16 v[58:59], v211 offset:45376
	ds_read_b64_tr_b16 v[68:69], v211 offset:47616
	ds_read_b64_tr_b16 v[70:71], v211 offset:48768
	ds_read_b64_tr_b16 v[74:75], v211 offset:48832
	ds_read_b64_tr_b16 v[72:73], v211 offset:47680
	ds_read_b64_tr_b16 v[84:85], v211 offset:49920
	ds_read_b64_tr_b16 v[86:87], v211 offset:51072
	ds_read_b64_tr_b16 v[90:91], v211 offset:51136
	ds_read_b64_tr_b16 v[88:89], v211 offset:49984
	s_waitcnt lgkmcnt(0)
	s_barrier
	v_mov_b64_e32 v[62:63], v[238:239]
	v_cvt_pk_bf16_f32 v53, v131, v135
	v_pk_mul_f32 v[14:15], v[14:15], v[0:1] op_sel_hi:[1,0]
	v_pk_mul_f32 v[12:13], v[12:13], v[0:1] op_sel_hi:[1,0]
	v_pk_mul_f32 v[10:11], v[10:11], v[0:1] op_sel_hi:[1,0]
	v_pk_mul_f32 v[8:9], v[8:9], v[0:1] op_sel_hi:[1,0]
	v_pk_mul_f32 v[6:7], v[6:7], v[0:1] op_sel_hi:[1,0]
	v_pk_mul_f32 v[4:5], v[4:5], v[0:1] op_sel_hi:[1,0]
	v_pk_mul_f32 v[2:3], v[2:3], v[0:1] op_sel_hi:[1,0]
	v_pk_add_f32 v[18:19], v[100:101], v[18:19]
	v_mfma_f32_32x32x16_bf16 v[34:49], v[20:23], v[50:53], v[34:49]
	v_add_f32_e64 v18, v102, v18
	v_add_f32_e64 v19, v103, v19
	v_sub_f32_e32 v20, v65, v96
	v_add_f32_e64 v18, v76, v18
	v_add_f32_e64 v19, v77, v19
	v_exp_f32_e32 v161, v20
	v_pk_add_f32 v[18:19], v[104:105], v[18:19]
	v_cvt_pk_bf16_f32 v20, v151, v155
	v_pk_add_f32 v[18:19], v[150:151], v[18:19]
	v_mfma_f32_32x32x16_bf16 v[2:17], v[24:27], v[50:53], v[2:17]
	v_mov_b64_e32 v[24:25], v[240:241]
	v_add_f32_e64 v18, v154, v18
	v_add_f32_e64 v19, v155, v19
	v_sub_f32_e32 v26, v30, v96
	v_add_f32_e64 v18, v158, v18
	v_add_f32_e64 v19, v159, v19
	v_cvt_pk_bf16_f32 v21, v159, v163
	v_pk_add_f32 v[18:19], v[162:163], v[18:19]
	v_cvt_pk_bf16_f32 v22, v83, v153
	v_cvt_pk_bf16_f32 v23, v157, v161
	v_exp_f32_e32 v67, v26
	v_mov_b64_e32 v[26:27], v[242:243]
	v_mfma_f32_32x32x16_bf16 v[34:49], v[54:57], v[20:23], v[34:49]
	v_sub_f32_e32 v30, v31, v96
	v_exp_f32_e32 v95, v30
	v_sub_f32_e32 v30, v32, v96
	v_exp_f32_e32 v93, v30
	v_sub_f32_e32 v30, v33, v96
	v_exp_f32_e32 v50, v30
	v_mov_b64_e32 v[30:31], v[244:245]
	v_mfma_f32_32x32x16_bf16 v[2:17], v[58:61], v[20:23], v[2:17]
	v_add_f32_e64 v22, v78, v18
	v_add_f32_e64 v23, v79, v19
	v_cvt_pk_bf16_f32 v18, v1, v125
	v_add_f32_e64 v22, v106, v22
	v_add_f32_e64 v23, v107, v23
	v_cvt_pk_bf16_f32 v19, v127, v129
	v_pk_add_f32 v[22:23], v[80:81], v[22:23]
	v_cvt_pk_bf16_f32 v20, v101, v103
	v_pk_add_f32 v[22:23], v[148:149], v[22:23]
	v_cvt_pk_bf16_f32 v21, v77, v105
	v_pk_add_f32 v[22:23], v[82:83], v[22:23]
	v_mov_b64_e32 v[32:33], v[246:247]
	v_pk_add_f32 v[22:23], v[152:153], v[22:23]
	v_mfma_f32_32x32x16_bf16 v[34:49], v[68:71], v[18:21], v[34:49]
	v_add_f32_e64 v22, v156, v22
	v_add_f32_e64 v23, v157, v23
	s_mov_b32 s0, s16
	v_add_f32_e64 v22, v160, v22
	v_add_f32_e64 v23, v161, v23
	v_writelane_b32 v255, s0, 35
	s_nop 1
	v_writelane_b32 v255, s1, 36
	v_mfma_f32_32x32x16_bf16 v[2:17], v[72:75], v[18:21], v[2:17]
	v_add_f32_e64 v18, v66, v22
	v_add_f32_e64 v19, v67, v23
	v_cvt_pk_bf16_f32 v20, v67, v95
	v_add_f32_e64 v18, v94, v18
	v_add_f32_e64 v19, v95, v19
	v_cvt_pk_bf16_f32 v21, v93, v50
	v_pk_add_f32 v[22:23], v[92:93], v[18:19]
	v_cvt_pk_bf16_f32 v18, v79, v107
	v_add_f32_e32 v23, v23, v50
	v_fmac_f32_e32 v23, v22, v0
	v_mov_b64_e32 v[0:1], v[248:249]
	v_cvt_pk_bf16_f32 v19, v81, v149
	ds_bpermute_b32 v22, v210, v23
	s_waitcnt lgkmcnt(0)
	v_add_f32_e32 v22, v23, v22
	v_mfma_f32_32x32x16_bf16 v[34:49], v[84:87], v[18:21], v[34:49]
	v_div_scale_f32 v23, s[0:1], v22, v22, 1.0
	v_rcp_f32_e32 v50, v23
	s_nop 0
	v_fma_f32 v51, -v23, v50, 1.0
	v_mfma_f32_32x32x16_bf16 v[2:17], v[88:91], v[18:21], v[2:17]
	v_mov_b64_e32 v[18:19], v[224:225]
	v_mov_b64_e32 v[20:21], v[226:227]
	v_fmac_f32_e32 v50, v51, v50
	v_div_scale_f32 v51, vcc, 1.0, v22, 1.0
	v_mul_f32_e32 v52, v51, v50
	v_fma_f32 v53, -v23, v52, v51
	v_fmac_f32_e32 v52, v53, v50
	v_fma_f32 v23, -v23, v52, v51
	v_div_fmas_f32 v23, v23, v50, v52
	v_div_fixup_f32 v22, v23, v22, 1.0
	v_pk_mul_f32 v[34:35], v[34:35], v[22:23] op_sel_hi:[1,0]
	s_waitcnt vmcnt(7)
	v_lshlrev_b32_e32 v50, 16, v62
	v_and_b32_e32 v51, 0xffff0000, v62
	v_pk_mul_f32 v[34:35], v[34:35], v[50:51]
	v_pk_mul_f32 v[36:37], v[36:37], v[22:23] op_sel_hi:[1,0]
	v_lshlrev_b32_e32 v50, 16, v63
	v_and_b32_e32 v51, 0xffff0000, v63
	v_pk_mul_f32 v[36:37], v[36:37], v[50:51]
	v_cvt_pk_bf16_f32 v34, v34, v35
	v_cvt_pk_bf16_f32 v35, v36, v37
	global_store_dwordx2 v[28:29], v[34:35], off
	v_pk_mul_f32 v[34:35], v[38:39], v[22:23] op_sel_hi:[1,0]
	s_waitcnt vmcnt(7)
	v_lshlrev_b32_e32 v36, 16, v24
	v_and_b32_e32 v37, 0xffff0000, v24
	v_pk_mul_f32 v[34:35], v[34:35], v[36:37]
	v_lshlrev_b32_e32 v36, 16, v25
	v_cvt_pk_bf16_f32 v24, v34, v35
	v_pk_mul_f32 v[34:35], v[40:41], v[22:23] op_sel_hi:[1,0]
	v_and_b32_e32 v37, 0xffff0000, v25
	v_pk_mul_f32 v[34:35], v[34:35], v[36:37]
	v_pk_mul_f32 v[2:3], v[2:3], v[22:23] op_sel_hi:[1,0]
	v_cvt_pk_bf16_f32 v25, v34, v35
	global_store_dwordx2 v[28:29], v[24:25], off offset:16
	v_pk_mul_f32 v[24:25], v[42:43], v[22:23] op_sel_hi:[1,0]
	s_waitcnt vmcnt(7)
	v_lshlrev_b32_e32 v34, 16, v26
	v_and_b32_e32 v35, 0xffff0000, v26
	v_pk_mul_f32 v[24:25], v[24:25], v[34:35]
	v_pk_mul_f32 v[34:35], v[44:45], v[22:23] op_sel_hi:[1,0]
	v_lshlrev_b32_e32 v26, 16, v27
	v_and_b32_e32 v27, 0xffff0000, v27
	v_pk_mul_f32 v[26:27], v[34:35], v[26:27]
	v_cvt_pk_bf16_f32 v24, v24, v25
	v_cvt_pk_bf16_f32 v25, v26, v27
	global_store_dwordx2 v[28:29], v[24:25], off offset:32
	v_pk_mul_f32 v[24:25], v[46:47], v[22:23] op_sel_hi:[1,0]
	s_waitcnt vmcnt(7)
	v_lshlrev_b32_e32 v26, 16, v30
	v_and_b32_e32 v27, 0xffff0000, v30
	v_pk_mul_f32 v[24:25], v[24:25], v[26:27]
	v_pk_mul_f32 v[26:27], v[48:49], v[22:23] op_sel_hi:[1,0]
	v_lshlrev_b32_e32 v30, 16, v31
	v_and_b32_e32 v31, 0xffff0000, v31
	v_pk_mul_f32 v[26:27], v[26:27], v[30:31]
	v_cvt_pk_bf16_f32 v24, v24, v25
	v_cvt_pk_bf16_f32 v25, v26, v27
	global_store_dwordx2 v[28:29], v[24:25], off offset:48
	s_waitcnt vmcnt(7)
	v_lshlrev_b32_e32 v24, 16, v32
	v_and_b32_e32 v25, 0xffff0000, v32
	v_pk_mul_f32 v[2:3], v[2:3], v[24:25]
	v_pk_mul_f32 v[4:5], v[4:5], v[22:23] op_sel_hi:[1,0]
	v_lshlrev_b32_e32 v24, 16, v33
	v_and_b32_e32 v25, 0xffff0000, v33
	v_pk_mul_f32 v[4:5], v[4:5], v[24:25]
	v_cvt_pk_bf16_f32 v2, v2, v3
	v_cvt_pk_bf16_f32 v3, v4, v5
	global_store_dwordx2 v[28:29], v[2:3], off offset:64
	v_pk_mul_f32 v[2:3], v[6:7], v[22:23] op_sel_hi:[1,0]
	s_waitcnt vmcnt(7)
	v_lshlrev_b32_e32 v4, 16, v0
	v_and_b32_e32 v5, 0xffff0000, v0
	v_pk_mul_f32 v[2:3], v[2:3], v[4:5]
	v_lshlrev_b32_e32 v4, 16, v1
	v_cvt_pk_bf16_f32 v0, v2, v3
	v_pk_mul_f32 v[2:3], v[8:9], v[22:23] op_sel_hi:[1,0]
	v_and_b32_e32 v5, 0xffff0000, v1
	v_pk_mul_f32 v[2:3], v[2:3], v[4:5]
	s_waitcnt vmcnt(6)
	v_lshlrev_b32_e32 v4, 16, v19
	v_cvt_pk_bf16_f32 v1, v2, v3
	global_store_dwordx2 v[28:29], v[0:1], off offset:80
	v_pk_mul_f32 v[0:1], v[10:11], v[22:23] op_sel_hi:[1,0]
	v_lshlrev_b32_e32 v2, 16, v18
	v_and_b32_e32 v3, 0xffff0000, v18
	v_pk_mul_f32 v[0:1], v[0:1], v[2:3]
	v_pk_mul_f32 v[2:3], v[12:13], v[22:23] op_sel_hi:[1,0]
	v_and_b32_e32 v5, 0xffff0000, v19
	v_pk_mul_f32 v[2:3], v[2:3], v[4:5]
	v_cvt_pk_bf16_f32 v0, v0, v1
	v_cvt_pk_bf16_f32 v1, v2, v3
	global_store_dwordx2 v[28:29], v[0:1], off offset:96
	v_pk_mul_f32 v[0:1], v[14:15], v[22:23] op_sel_hi:[1,0]
	s_waitcnt vmcnt(7)
	v_lshlrev_b32_e32 v2, 16, v20
	v_and_b32_e32 v3, 0xffff0000, v20
	v_pk_mul_f32 v[0:1], v[0:1], v[2:3]
	v_pk_mul_f32 v[2:3], v[16:17], v[22:23] op_sel_hi:[1,0]
	v_lshlrev_b32_e32 v4, 16, v21
	v_and_b32_e32 v5, 0xffff0000, v21
	v_pk_mul_f32 v[2:3], v[2:3], v[4:5]
	v_cvt_pk_bf16_f32 v0, v0, v1
	v_cvt_pk_bf16_f32 v1, v2, v3
	global_store_dwordx2 v[28:29], v[0:1], off offset:112

.LBB0_1410:
	v_mov_b32_e32 v230, 0x800
	v_mov_b32_e32 v231, 0x100
	v_mov_b32_e32 v232, 0x7ff
	v_mov_b32_e32 v233, 0xff
	s_mov_b32 s0, 0x60000
	v_cmp_gt_i32_e32 vcc, s0, v14
	s_and_saveexec_b64 s[0:1], vcc
	s_cbranch_execz .LBB0_1432
	s_add_u32 s18, s46, 0xa3fe000
	s_addc_u32 s19, s47, 0
	s_add_u32 s20, s46, 0x8bfe600
	s_addc_u32 s21, s47, 0
	s_mov_b64 s[36:37], 0
	v_mov_b32_e32 v15, v14
	s_branch .LBB0_1414

.LBB0_1432:
	s_or_b64 exec, exec, s[0:1]
	v_readlane_b32 s0, v253, 2
	v_readlane_b32 s1, v253, 3
	s_and_b64 s[0:1], s[0:1], s[30:31]
	s_and_b64 vcc, exec, s[0:1]
	s_cbranch_vccz .LBB0_1446
	v_readfirstlane_b32 s0, v14
	s_cmp_gt_u32 s0, 0x63fff
	s_cbranch_scc1 .LBB0_1446
	v_lshlrev_b32_e32 v192, 6, v213
	v_lshl_add_u64 v[64:65], s[46:47], 0, v[192:193]
	v_add_co_u32_e32 v8, vcc, 0x1ef000, v64
	s_mov_b32 s1, 0x1f2000
	s_nop 0
	v_addc_co_u32_e32 v9, vcc, 0, v65, vcc
	v_add_co_u32_e32 v24, vcc, s1, v64
	s_mov_b32 s1, 0x1f5000
	s_nop 0
	v_addc_co_u32_e32 v25, vcc, 0, v65, vcc
	s_mov_b64 s[4:5], 0x1ef000
	v_add_co_u32_e32 v40, vcc, s1, v64
	v_lshl_add_u64 v[12:13], v[64:65], 0, s[4:5]
	s_mov_b64 s[4:5], 0x1f2000
	v_addc_co_u32_e32 v41, vcc, 0, v65, vcc
	s_mov_b32 s1, 0x1f8000
	v_lshl_add_u64 v[28:29], v[64:65], 0, s[4:5]
	s_mov_b64 s[4:5], 0x1f5000
	v_add_co_u32_e32 v56, vcc, s1, v64
	v_lshl_add_u64 v[44:45], v[64:65], 0, s[4:5]
	s_mov_b64 s[4:5], 0x1f8000
	v_addc_co_u32_e32 v57, vcc, 0, v65, vcc
	s_mov_b32 s1, 0x1fb000
	v_lshl_add_u64 v[60:61], v[64:65], 0, s[4:5]
	s_mov_b64 s[4:5], 0x1fb000
	v_add_co_u32_e32 v72, vcc, s1, v64
	v_lshl_add_u64 v[76:77], v[64:65], 0, s[4:5]
	s_nop 0
	v_addc_co_u32_e32 v73, vcc, 0, v65, vcc
	global_load_dwordx4 v[0:3], v[12:13], off offset:16
	global_load_dwordx4 v[4:7], v[12:13], off offset:32
	s_waitcnt lgkmcnt(0)
	global_load_dwordx4 v[8:11], v[8:9], off
	s_nop 0
	global_load_dwordx4 v[12:15], v[12:13], off offset:48
	s_nop 0
	global_load_dwordx4 v[16:19], v[28:29], off offset:16
	global_load_dwordx4 v[20:23], v[28:29], off offset:32
	s_nop 0
	global_load_dwordx4 v[24:27], v[24:25], off
	s_nop 0
	global_load_dwordx4 v[28:31], v[28:29], off offset:48
	s_nop 0
	global_load_dwordx4 v[32:35], v[44:45], off offset:16
	global_load_dwordx4 v[36:39], v[44:45], off offset:32
	s_nop 0
	global_load_dwordx4 v[40:43], v[40:41], off
	s_nop 0
	global_load_dwordx4 v[44:47], v[44:45], off offset:48
	s_nop 0
	global_load_dwordx4 v[48:51], v[60:61], off offset:16
	global_load_dwordx4 v[52:55], v[60:61], off offset:32
	s_nop 0
	global_load_dwordx4 v[56:59], v[56:57], off
	s_nop 0
	global_load_dwordx4 v[60:63], v[60:61], off offset:48
	s_nop 0
	global_load_dwordx4 v[64:67], v[76:77], off offset:16
	global_load_dwordx4 v[68:71], v[76:77], off offset:32
	s_nop 0
	global_load_dwordx4 v[72:75], v[72:73], off
	s_nop 0
	global_load_dwordx4 v[76:79], v[76:77], off offset:48
	v_cmp_lt_i32_e32 vcc, v222, v221
	s_lshr_b32 s12, s0, 6
	s_lshl_b64 s[0:1], s[12:13], 11
	v_cndmask_b32_e32 v80, v220, v222, vcc
	v_cmp_lt_i32_e32 vcc, v223, v221
	v_lshlrev_b32_e32 v82, 2, v80
	v_cmp_eq_u32_e64 s[38:39], 0, v213
	v_cndmask_b32_e32 v80, v220, v223, vcc
	v_cmp_lt_i32_e32 vcc, v251, v221
	v_lshlrev_b32_e32 v83, 2, v80
	s_lshl_b32 s4, s12, 2
	v_cndmask_b32_e32 v80, v220, v251, vcc
	v_cmp_lt_i32_e32 vcc, v252, v221
	v_lshlrev_b32_e32 v84, 2, v80
	s_mov_b32 s5, s13
	v_cndmask_b32_e32 v80, v220, v252, vcc
	v_lshlrev_b32_e32 v85, 2, v80
	v_xor_b32_e32 v80, 2, v220
	v_cmp_lt_i32_e32 vcc, v80, v221
	v_mov_b32_e32 v81, s1
	s_nop 0
	v_cndmask_b32_e32 v80, v220, v80, vcc
	v_lshlrev_b32_e32 v86, 2, v80
	v_xor_b32_e32 v80, 1, v220
	v_cmp_lt_i32_e32 vcc, v80, v221
	s_nop 1
	v_cndmask_b32_e32 v80, v220, v80, vcc
	v_lshlrev_b32_e32 v87, 2, v80
	v_lshl_or_b32 v80, v213, 5, s0
	v_lshl_add_u64 v[126:127], s[46:47], 0, v[80:81]
	s_mov_b64 s[0:1], 0xf7e000
	v_lshl_add_u64 v[126:127], v[126:127], 0, s[0:1]
	global_load_dwordx4 v[118:121], v[126:127], off
	global_load_dwordx4 v[122:125], v[126:127], off offset:16
	v_mov_b32_e32 v214, 0xf20e000
	v_mov_b32_e32 v215, 0xf214000
	v_mov_b32_e32 v216, 0xf21a000
	v_mov_b32_e32 v217, 0xf220000
	s_branch .LBB0_1436

.LBB0_1436:
	s_waitcnt lgkmcnt(0)
	s_waitcnt vmcnt(0)
	v_lshlrev_b32_e32 v96, 16, v118
	v_and_b32_e32 v94, 0xffff0000, v118
	v_lshlrev_b32_e32 v93, 16, v119
	v_and_b32_e32 v92, 0xffff0000, v119
	v_lshlrev_b32_e32 v91, 16, v120
	v_and_b32_e32 v90, 0xffff0000, v120
	v_lshlrev_b32_e32 v89, 16, v121
	v_and_b32_e32 v88, 0xffff0000, v121
	v_lshlrev_b32_e32 v102, 16, v122
	v_and_b32_e32 v101, 0xffff0000, v122
	v_lshlrev_b32_e32 v100, 16, v123
	v_and_b32_e32 v99, 0xffff0000, v123
	v_lshlrev_b32_e32 v98, 16, v124
	v_and_b32_e32 v97, 0xffff0000, v124
	v_lshlrev_b32_e32 v95, 16, v125
	v_and_b32_e32 v103, 0xffff0000, v125
	s_add_i32 s10, s12, s96
	s_cmpk_lt_u32 s10, 0x1900
	s_cbranch_scc0 .Lsw_nopf
	v_readlane_b32 s0, v255, 39
	v_readlane_b32 s1, v255, 40
	s_nop 1
	v_lshl_add_u64 v[126:127], v[80:81], 0, s[0:1]
	v_lshl_add_u64 v[126:127], s[46:47], 0, v[126:127]
	s_mov_b64 s[0:1], 0xf7e000
	v_lshl_add_u64 v[126:127], v[126:127], 0, s[0:1]
	global_load_dwordx4 v[118:121], v[126:127], off
	global_load_dwordx4 v[122:125], v[126:127], off offset:16
.Lsw_nopf:
	v_fma_f32 v108, v8, v96, 0
	v_fmac_f32_e32 v108, v9, v94
	v_fmac_f32_e32 v108, v10, v93
	v_fmac_f32_e32 v108, v11, v92
	v_fmac_f32_e32 v108, v0, v91
	v_fmac_f32_e32 v108, v1, v90
	v_fmac_f32_e32 v108, v2, v89
	v_fmac_f32_e32 v108, v3, v88
	v_fmac_f32_e32 v108, v4, v102
	v_fmac_f32_e32 v108, v5, v101
	v_fmac_f32_e32 v108, v6, v100
	v_fmac_f32_e32 v108, v7, v99
	v_fmac_f32_e32 v108, v12, v98
	v_fmac_f32_e32 v108, v13, v97
	v_fmac_f32_e32 v108, v14, v95
	v_fmac_f32_e32 v108, v15, v103
	v_fma_f32 v109, v24, v96, 0
	v_fmac_f32_e32 v109, v25, v94
	v_fmac_f32_e32 v109, v26, v93
	v_fmac_f32_e32 v109, v27, v92
	v_fmac_f32_e32 v109, v16, v91
	v_fmac_f32_e32 v109, v17, v90
	v_fmac_f32_e32 v109, v18, v89
	v_fmac_f32_e32 v109, v19, v88
	v_fmac_f32_e32 v109, v20, v102
	v_fmac_f32_e32 v109, v21, v101
	v_fmac_f32_e32 v109, v22, v100
	v_fmac_f32_e32 v109, v23, v99
	v_fmac_f32_e32 v109, v28, v98
	v_fmac_f32_e32 v109, v29, v97
	v_fmac_f32_e32 v109, v30, v95
	v_fmac_f32_e32 v109, v31, v103
	v_fma_f32 v110, v40, v96, 0
	v_fmac_f32_e32 v110, v41, v94
	v_fmac_f32_e32 v110, v42, v93
	v_fmac_f32_e32 v110, v43, v92
	v_fmac_f32_e32 v110, v32, v91
	v_fmac_f32_e32 v110, v33, v90
	v_fmac_f32_e32 v110, v34, v89
	v_fmac_f32_e32 v110, v35, v88
	v_fmac_f32_e32 v110, v36, v102
	v_fmac_f32_e32 v110, v37, v101
	v_fmac_f32_e32 v110, v38, v100
	v_fmac_f32_e32 v110, v39, v99
	v_fmac_f32_e32 v110, v44, v98
	v_fmac_f32_e32 v110, v45, v97
	v_fmac_f32_e32 v110, v46, v95
	v_fmac_f32_e32 v110, v47, v103
	v_fma_f32 v111, v56, v96, 0
	v_fmac_f32_e32 v111, v57, v94
	v_fmac_f32_e32 v111, v58, v93
	v_fmac_f32_e32 v111, v59, v92
	v_fmac_f32_e32 v111, v48, v91
	v_fmac_f32_e32 v111, v49, v90
	v_fmac_f32_e32 v111, v50, v89
	v_fmac_f32_e32 v111, v51, v88
	v_fmac_f32_e32 v111, v52, v102
	v_fmac_f32_e32 v111, v53, v101
	v_fmac_f32_e32 v111, v54, v100
	v_fmac_f32_e32 v111, v55, v99
	v_fmac_f32_e32 v111, v60, v98
	v_fmac_f32_e32 v111, v61, v97
	v_fmac_f32_e32 v111, v62, v95
	v_fmac_f32_e32 v111, v63, v103
	v_fma_f32 v112, v72, v96, 0
	v_fmac_f32_e32 v112, v73, v94
	v_fmac_f32_e32 v112, v74, v93
	v_fmac_f32_e32 v112, v75, v92
	v_fmac_f32_e32 v112, v64, v91
	v_fmac_f32_e32 v112, v65, v90
	v_fmac_f32_e32 v112, v66, v89
	v_fmac_f32_e32 v112, v67, v88
	v_fmac_f32_e32 v112, v68, v102
	v_fmac_f32_e32 v112, v69, v101
	v_fmac_f32_e32 v112, v70, v100
	v_fmac_f32_e32 v112, v71, v99
	v_fmac_f32_e32 v112, v76, v98
	v_fmac_f32_e32 v112, v77, v97
	v_fmac_f32_e32 v112, v78, v95
	v_fmac_f32_e32 v112, v79, v103
	ds_bpermute_b32 v113, v82, v108
	ds_bpermute_b32 v114, v82, v109
	ds_bpermute_b32 v115, v82, v110
	ds_bpermute_b32 v116, v82, v111
	ds_bpermute_b32 v117, v82, v112
	s_waitcnt lgkmcnt(0)
	v_add_f32_e32 v108, v108, v113
	v_add_f32_e32 v109, v109, v114
	v_add_f32_e32 v110, v110, v115
	v_add_f32_e32 v111, v111, v116
	v_add_f32_e32 v112, v112, v117
	ds_bpermute_b32 v113, v83, v108
	ds_bpermute_b32 v114, v83, v109
	ds_bpermute_b32 v115, v83, v110
	ds_bpermute_b32 v116, v83, v111
	ds_bpermute_b32 v117, v83, v112
	s_waitcnt lgkmcnt(0)
	v_add_f32_e32 v108, v108, v113
	v_add_f32_e32 v109, v109, v114
	v_add_f32_e32 v110, v110, v115
	v_add_f32_e32 v111, v111, v116
	v_add_f32_e32 v112, v112, v117
	ds_bpermute_b32 v113, v84, v108
	ds_bpermute_b32 v114, v84, v109
	ds_bpermute_b32 v115, v84, v110
	ds_bpermute_b32 v116, v84, v111
	ds_bpermute_b32 v117, v84, v112
	s_waitcnt lgkmcnt(0)
	v_add_f32_e32 v108, v108, v113
	v_add_f32_e32 v109, v109, v114
	v_add_f32_e32 v110, v110, v115
	v_add_f32_e32 v111, v111, v116
	v_add_f32_e32 v112, v112, v117
	ds_bpermute_b32 v113, v85, v108
	ds_bpermute_b32 v114, v85, v109
	ds_bpermute_b32 v115, v85, v110
	ds_bpermute_b32 v116, v85, v111
	ds_bpermute_b32 v117, v85, v112
	s_waitcnt lgkmcnt(0)
	v_add_f32_e32 v108, v108, v113
	v_add_f32_e32 v109, v109, v114
	v_add_f32_e32 v110, v110, v115
	v_add_f32_e32 v111, v111, v116
	v_add_f32_e32 v112, v112, v117
	ds_bpermute_b32 v113, v86, v108
	ds_bpermute_b32 v114, v86, v109
	ds_bpermute_b32 v115, v86, v110
	ds_bpermute_b32 v116, v86, v111
	ds_bpermute_b32 v117, v86, v112
	s_waitcnt lgkmcnt(0)
	v_add_f32_e32 v108, v108, v113
	v_add_f32_e32 v109, v109, v114
	v_add_f32_e32 v110, v110, v115
	v_add_f32_e32 v111, v111, v116
	v_add_f32_e32 v112, v112, v117
	ds_bpermute_b32 v113, v87, v108
	ds_bpermute_b32 v114, v87, v109
	ds_bpermute_b32 v115, v87, v110
	ds_bpermute_b32 v116, v87, v111
	ds_bpermute_b32 v117, v87, v112
	s_waitcnt lgkmcnt(0)
	v_add_f32_e32 v108, v108, v113
	v_add_f32_e32 v109, v109, v114
	v_add_f32_e32 v110, v110, v115
	v_add_f32_e32 v111, v111, v116
	v_add_f32_e32 v112, v112, v117
	s_and_saveexec_b64 s[0:1], s[38:39]
	s_add_u32 s10, s46, s4
	s_addc_u32 s11, s47, s5
	global_store_dword v214, v108, s[10:11]
	global_store_dword v215, v109, s[10:11] offset:1024
	global_store_dword v216, v110, s[10:11] offset:2048
	global_store_dword v217, v111, s[10:11] offset:3072
	global_store_dword v218, v112, s[10:11]
	s_branch .LBB0_1435
